# first K-loop iteration of the P1/P4/P5/P7 GEMM loops peeled: the first MFMA of each accumulator takes srcC = 0, the 64 v_mov_b64 accumulator clears per tile header are gone
# speedup vs baseline: 1.0069x; 1.0004x over previous
; #define PG8_STAGE(bufoff, gbase, voff) do { _Pragma("unroll") for (int _i = 0; _i < 2; ++_i) \
;         __builtin_amdgcn_global_load_lds((const __attribute__((address_space(1))) unsigned*)((const char*)(gbase) + (voff)[_i]), (LAS unsigned*)(lds + (bufoff) + ldsw + _i * 8192), 16, 0, 0); } while (0)
; #define PG8_LDA(dst, b, h) do { _Pragma("unroll") for (int m = 0; m < 4; ++m) _Pragma("unroll") for (int k = 0; k < 2; ++k) dst[m][k] = *(const LAS bf16x8*)(lds + PG8_SA(b, h) + aoff + m * 2048 + k * 1024); } while (0)
; #define PG8_LDB(dst, b, h) do { _Pragma("unroll") for (int n = 0; n < 2; ++n) _Pragma("unroll") for (int k = 0; k < 2; ++k) dst[n][k] = *(const LAS bf16x8*)(lds + PG8_SB(b, h) + boff + n * 2048 + k * 1024); } while (0)
; #define PG8_MMA(ai, bj, At, Bt) do { __builtin_amdgcn_s_setprio(1); _Pragma("unroll") for (int m = 0; m < 4; ++m) _Pragma("unroll") for (int n = 0; n < 2; ++n) _Pragma("unroll") for (int k = 0; k < 2; ++k) \
;         acc[ai][bj][m][n] = __builtin_amdgcn_mfma_f32_16x16x32_bf16(Bt[n][k], At[m][k], acc[ai][bj][m][n], 0, 0, 0); __builtin_amdgcn_s_setprio(0); } while (0)
; #define PG8_WAIT_V(n) asm volatile("s_waitcnt vmcnt(" #n ")" ::: "memory")
; #define PG8_WAIT_L(n) asm volatile("s_waitcnt lgkmcnt(" #n ")" ::: "memory")
; #define PG8_BAR __builtin_amdgcn_s_barrier()
; #define PG8_SCHED __builtin_amdgcn_sched_barrier(0)
; template <class Epi, class SchedT, bool ALIGN_EPI, bool SP2>
; __device__ __forceinline__ void gemm_phase(LAS unsigned char* lds, const int ldk, const int nt, const SchedT& S, const Epi& E) {
;     ...
;             PG8_LDB(B0, 0, 0); PG8_LDB(B1, 0, 1); PG8_SCHED; PG8_LDA(At, 0, 0); PG8_STAGE(PG8_SA(1, 1), a1 + hstep, voffA);
;             PG8_WAIT_V(8); PG8_WAIT_L(0); PG8_BAR; PG8_MMA(0, 0, At, B0); PG8_MMA(0, 1, At, B1); PG8_BAR; PG8_SCHED;
;             PG8_LDA(At, 0, 1); PG8_STAGE(PG8_SB(0, 0), b2, voffB); PG8_STAGE(PG8_SB(0, 1), b2 + hstepB, voffB); PG8_STAGE(PG8_SA(0, 0), a2, voffA);
;     ...
; #pragma unroll
;         for (int a = 0; a < 2; ++a)
; #pragma unroll
;             for (int b = 0; b < 2; ++b)
; #pragma unroll
;                 for (int m = 0; m < 4; ++m)
; #pragma unroll
;                     for (int n = 0; n < 2; ++n) acc[a][b][m][n] = (f32x4){0.f, 0.f, 0.f, 0.f};
;         }
.LBB0_122:
	s_add_u32 s0, s12, 0x80080
	s_addc_u32 s1, s13, 0
	s_add_u32 s18, s16, 0x100
	s_addc_u32 s19, s17, 0
	s_mov_b32 s21, -2
	s_add_u32 s12, s0, 0xfff80080
	s_addc_u32 s13, s1, -1
	s_add_i32 s34, 0, 0x10000
	s_cmp_eq_u32 s21, 28
	s_cselect_b32 s17, s61, s13
	s_cselect_b32 s16, s60, s12
	v_add_u32_e32 v0, s34, v212
	s_cselect_b32 s13, s31, s19
	s_cselect_b32 s12, s30, s18
	s_add_i32 s38, 0, 0x14000
	s_waitcnt lgkmcnt(0)
	ds_read_b128 v[132:135], v0
	ds_read_b128 v[136:139], v0 offset:1024
	ds_read_b128 v[140:143], v0 offset:2048
	ds_read_b128 v[144:147], v0 offset:3072
	v_add_u32_e32 v0, s38, v212
	ds_read_b128 v[148:151], v0
	ds_read_b128 v[152:155], v0 offset:1024
	ds_read_b128 v[184:187], v0 offset:2048
	ds_read_b128 v[188:191], v0 offset:3072
	v_lshl_add_u64 v[2:3], s[0:1], 0, v[180:181]
	s_add_i32 m0, s88, 0xc000
	ds_read_b128 v[192:195], v216
	ds_read_b128 v[196:199], v216 offset:1024
	ds_read_b128 v[200:203], v216 offset:2048
	ds_read_b128 v[204:207], v216 offset:3072
	ds_read_b128 v[218:221], v216 offset:4096
	ds_read_b128 v[222:225], v216 offset:5120
	ds_read_b128 v[226:229], v216 offset:6144
	ds_read_b128 v[230:233], v216 offset:7168
	global_load_lds_dwordx4 v[2:3], off
	v_lshl_add_u64 v[2:3], s[0:1], 0, v[182:183]
	s_add_i32 m0, s88, 0xe000
	s_nop 0
	global_load_lds_dwordx4 v[2:3], off
	s_waitcnt vmcnt(8)
	s_waitcnt lgkmcnt(0)
	s_barrier
	s_waitcnt lgkmcnt(0)
	v_mfma_f32_16x16x32_bf16 v[128:131], v[132:135], v[192:195], 0
	v_mfma_f32_16x16x32_bf16 v[124:127], v[140:143], v[192:195], 0
	v_mfma_f32_16x16x32_bf16 v[112:115], v[132:135], v[200:203], 0
	v_mfma_f32_16x16x32_bf16 v[108:111], v[140:143], v[200:203], 0
	v_mfma_f32_16x16x32_bf16 v[96:99], v[132:135], v[218:221], 0
	v_mfma_f32_16x16x32_bf16 v[92:95], v[140:143], v[218:221], 0
	v_mfma_f32_16x16x32_bf16 v[80:83], v[132:135], v[226:229], 0
	v_mfma_f32_16x16x32_bf16 v[76:79], v[140:143], v[226:229], 0
	v_mfma_f32_16x16x32_bf16 v[128:131], v[136:139], v[196:199], v[128:131]
	v_mfma_f32_16x16x32_bf16 v[124:127], v[144:147], v[196:199], v[124:127]
	v_mfma_f32_16x16x32_bf16 v[112:115], v[136:139], v[204:207], v[112:115]
	v_mfma_f32_16x16x32_bf16 v[108:111], v[144:147], v[204:207], v[108:111]
	v_mfma_f32_16x16x32_bf16 v[96:99], v[136:139], v[222:225], v[96:99]
	v_mfma_f32_16x16x32_bf16 v[92:95], v[144:147], v[222:225], v[92:95]
	v_mfma_f32_16x16x32_bf16 v[80:83], v[136:139], v[230:233], v[80:83]
	v_mfma_f32_16x16x32_bf16 v[76:79], v[144:147], v[230:233], v[76:79]
	v_mfma_f32_16x16x32_bf16 v[120:123], v[148:151], v[192:195], 0
	v_mfma_f32_16x16x32_bf16 v[116:119], v[184:187], v[192:195], 0
	v_mfma_f32_16x16x32_bf16 v[104:107], v[148:151], v[200:203], 0
	v_mfma_f32_16x16x32_bf16 v[100:103], v[184:187], v[200:203], 0
	v_mfma_f32_16x16x32_bf16 v[88:91], v[148:151], v[218:221], 0
	v_mfma_f32_16x16x32_bf16 v[84:87], v[184:187], v[218:221], 0
	v_mfma_f32_16x16x32_bf16 v[72:75], v[148:151], v[226:229], 0
	v_mfma_f32_16x16x32_bf16 v[68:71], v[184:187], v[226:229], 0
	v_mfma_f32_16x16x32_bf16 v[120:123], v[152:155], v[196:199], v[120:123]
	v_mfma_f32_16x16x32_bf16 v[116:119], v[188:191], v[196:199], v[116:119]
	v_mfma_f32_16x16x32_bf16 v[104:107], v[152:155], v[204:207], v[104:107]
	v_mfma_f32_16x16x32_bf16 v[100:103], v[188:191], v[204:207], v[100:103]
	v_mfma_f32_16x16x32_bf16 v[88:91], v[152:155], v[222:225], v[88:91]
	v_mfma_f32_16x16x32_bf16 v[84:87], v[188:191], v[222:225], v[84:87]
	v_mfma_f32_16x16x32_bf16 v[72:75], v[152:155], v[230:233], v[72:75]
	v_mfma_f32_16x16x32_bf16 v[68:71], v[188:191], v[230:233], v[68:71]
	s_barrier
	s_add_i32 s34, s34, s87
	v_lshl_add_u64 v[208:209], s[12:13], 0, v[158:159]
	s_mov_b32 m0, s34
	ds_read_b128 v[192:195], v216 offset:16384
	ds_read_b128 v[196:199], v216 offset:17408
	ds_read_b128 v[200:203], v216 offset:18432
	ds_read_b128 v[204:207], v216 offset:19456
	ds_read_b128 v[218:221], v216 offset:20480
	ds_read_b128 v[222:225], v216 offset:21504
	ds_read_b128 v[226:229], v216 offset:22528
	ds_read_b128 v[230:233], v216 offset:23552
	global_load_lds_dwordx4 v[208:209], off
	s_add_i32 m0, s34, 0x2000
	s_add_u32 s34, s12, 0x20000
	v_lshl_add_u64 v[234:235], s[12:13], 0, v[174:175]
	s_addc_u32 s35, s13, 0
	s_add_i32 s38, s38, s87
	global_load_lds_dwordx4 v[234:235], off
	v_lshl_add_u64 v[2:3], s[34:35], 0, v[158:159]
	s_mov_b32 m0, s38
	v_lshl_add_u64 v[236:237], s[16:17], 0, v[156:157]
	global_load_lds_dwordx4 v[2:3], off
	v_lshl_add_u64 v[2:3], s[34:35], 0, v[174:175]
	s_add_i32 m0, s38, 0x2000
	v_lshl_add_u64 v[238:239], s[16:17], 0, v[160:161]
	global_load_lds_dwordx4 v[2:3], off
	s_mov_b32 m0, s88
	s_nop 0
	global_load_lds_dwordx4 v[236:237], off
	s_mov_b32 m0, s89
	s_nop 0
	global_load_lds_dwordx4 v[238:239], off
	s_waitcnt vmcnt(8)
	s_waitcnt lgkmcnt(0)
	s_barrier
; #define PG8_STAGE(bufoff, gbase, voff) do { _Pragma("unroll") for (int _i = 0; _i < 2; ++_i) \
;         __builtin_amdgcn_global_load_lds((const __attribute__((address_space(1))) unsigned*)((const char*)(gbase) + (voff)[_i]), (LAS unsigned*)(lds + (bufoff) + ldsw + _i * 8192), 16, 0, 0); } while (0)
; #define PG8_LDA(dst, b, h) do { _Pragma("unroll") for (int m = 0; m < 4; ++m) _Pragma("unroll") for (int k = 0; k < 2; ++k) dst[m][k] = *(const LAS bf16x8*)(lds + PG8_SA(b, h) + aoff + m * 2048 + k * 1024); } while (0)
; #define PG8_LDB(dst, b, h) do { _Pragma("unroll") for (int n = 0; n < 2; ++n) _Pragma("unroll") for (int k = 0; k < 2; ++k) dst[n][k] = *(const LAS bf16x8*)(lds + PG8_SB(b, h) + boff + n * 2048 + k * 1024); } while (0)
; #define PG8_MMA(ai, bj, At, Bt) do { __builtin_amdgcn_s_setprio(1); _Pragma("unroll") for (int m = 0; m < 4; ++m) _Pragma("unroll") for (int n = 0; n < 2; ++n) _Pragma("unroll") for (int k = 0; k < 2; ++k) \
;         acc[ai][bj][m][n] = __builtin_amdgcn_mfma_f32_16x16x32_bf16(Bt[n][k], At[m][k], acc[ai][bj][m][n], 0, 0, 0); __builtin_amdgcn_s_setprio(0); } while (0)
; #define PG8_WAIT_V(n) asm volatile("s_waitcnt vmcnt(" #n ")" ::: "memory")
; #define PG8_WAIT_L(n) asm volatile("s_waitcnt lgkmcnt(" #n ")" ::: "memory")
; #define PG8_BAR __builtin_amdgcn_s_barrier()
; #define PG8_SCHED __builtin_amdgcn_sched_barrier(0)
; template <class Epi, class SchedT, bool ALIGN_EPI, bool SP2>
; __device__ __forceinline__ void gemm_phase(LAS unsigned char* lds, const int ldk, const int nt, const SchedT& S, const Epi& E) {
;     ...
;             PG8_WAIT_V(8); PG8_WAIT_L(0); PG8_BAR; PG8_MMA(1, 0, At, B0); PG8_MMA(1, 1, At, B1); PG8_BAR; PG8_SCHED;
;             PG8_LDB(B0, 1, 0); PG8_LDB(B1, 1, 1); PG8_SCHED; PG8_LDA(At, 1, 0); PG8_STAGE(PG8_SA(0, 1), a2 + hstep, voffA);
;             PG8_WAIT_V(8); PG8_WAIT_L(0); PG8_BAR; PG8_MMA(0, 0, At, B0); PG8_MMA(0, 1, At, B1); PG8_BAR; PG8_SCHED;
	s_waitcnt lgkmcnt(0)
	v_mfma_f32_16x16x32_bf16 v[64:67], v[132:135], v[192:195], 0
	v_mfma_f32_16x16x32_bf16 v[60:63], v[140:143], v[192:195], 0
	v_mfma_f32_16x16x32_bf16 v[48:51], v[132:135], v[200:203], 0
	v_mfma_f32_16x16x32_bf16 v[44:47], v[140:143], v[200:203], 0
	v_mfma_f32_16x16x32_bf16 v[32:35], v[132:135], v[218:221], 0
	v_mfma_f32_16x16x32_bf16 v[28:31], v[140:143], v[218:221], 0
	v_mfma_f32_16x16x32_bf16 v[16:19], v[132:135], v[226:229], 0
	v_mfma_f32_16x16x32_bf16 v[12:15], v[140:143], v[226:229], 0
	v_mfma_f32_16x16x32_bf16 v[64:67], v[136:139], v[196:199], v[64:67]
	v_mfma_f32_16x16x32_bf16 v[60:63], v[144:147], v[196:199], v[60:63]
	v_mfma_f32_16x16x32_bf16 v[48:51], v[136:139], v[204:207], v[48:51]
	v_mfma_f32_16x16x32_bf16 v[44:47], v[144:147], v[204:207], v[44:47]
	v_mfma_f32_16x16x32_bf16 v[32:35], v[136:139], v[222:225], v[32:35]
	v_mfma_f32_16x16x32_bf16 v[28:31], v[144:147], v[222:225], v[28:31]
	v_mfma_f32_16x16x32_bf16 v[16:19], v[136:139], v[230:233], v[16:19]
	v_mfma_f32_16x16x32_bf16 v[12:15], v[144:147], v[230:233], v[12:15]
	v_mfma_f32_16x16x32_bf16 v[56:59], v[148:151], v[192:195], 0
	v_mfma_f32_16x16x32_bf16 v[52:55], v[184:187], v[192:195], 0
	v_mfma_f32_16x16x32_bf16 v[40:43], v[148:151], v[200:203], 0
	v_mfma_f32_16x16x32_bf16 v[36:39], v[184:187], v[200:203], 0
	v_mfma_f32_16x16x32_bf16 v[24:27], v[148:151], v[218:221], 0
	v_mfma_f32_16x16x32_bf16 v[20:23], v[184:187], v[218:221], 0
	v_mfma_f32_16x16x32_bf16 v[8:11], v[148:151], v[226:229], 0
	v_mfma_f32_16x16x32_bf16 v[2:5], v[184:187], v[226:229], 0
	v_mfma_f32_16x16x32_bf16 v[56:59], v[152:155], v[196:199], v[56:59]
	v_mfma_f32_16x16x32_bf16 v[52:55], v[188:191], v[196:199], v[52:55]
	v_mfma_f32_16x16x32_bf16 v[40:43], v[152:155], v[204:207], v[40:43]
	v_mfma_f32_16x16x32_bf16 v[36:39], v[188:191], v[204:207], v[36:39]
	v_mfma_f32_16x16x32_bf16 v[24:27], v[152:155], v[222:225], v[24:27]
	v_mfma_f32_16x16x32_bf16 v[20:23], v[188:191], v[222:225], v[20:23]
	v_mfma_f32_16x16x32_bf16 v[8:11], v[152:155], v[230:233], v[8:11]
	v_mfma_f32_16x16x32_bf16 v[2:5], v[188:191], v[230:233], v[2:5]
	s_barrier
	s_add_i32 s34, 0, 0x18000
	v_add_u32_e32 v0, s34, v212
	s_add_i32 s35, 0, 0x1c000
	ds_read_b128 v[132:135], v0
	ds_read_b128 v[136:139], v0 offset:1024
	ds_read_b128 v[140:143], v0 offset:2048
	ds_read_b128 v[144:147], v0 offset:3072
	v_add_u32_e32 v0, s35, v212
	ds_read_b128 v[148:151], v0
	ds_read_b128 v[152:155], v0 offset:1024
	ds_read_b128 v[184:187], v0 offset:2048
	ds_read_b128 v[188:191], v0 offset:3072
	s_add_u32 s16, s16, 0x80000
	s_addc_u32 s17, s17, 0
	s_mov_b32 m0, s90
	v_lshl_add_u64 v[6:7], s[16:17], 0, v[156:157]
	ds_read_b128 v[192:195], v216 offset:32768
	ds_read_b128 v[196:199], v216 offset:33792
	ds_read_b128 v[200:203], v216 offset:34816
	ds_read_b128 v[204:207], v216 offset:35840
	ds_read_b128 v[218:221], v216 offset:36864
	ds_read_b128 v[222:225], v216 offset:37888
	ds_read_b128 v[226:229], v216 offset:38912
	ds_read_b128 v[230:233], v216 offset:39936
	global_load_lds_dwordx4 v[6:7], off
	v_lshl_add_u64 v[6:7], s[16:17], 0, v[160:161]
	s_mov_b32 m0, s91
	s_nop 0
	global_load_lds_dwordx4 v[6:7], off
	s_waitcnt vmcnt(8)
	s_waitcnt lgkmcnt(0)
	s_barrier
	s_waitcnt lgkmcnt(0)
	v_mfma_f32_16x16x32_bf16 v[128:131], v[132:135], v[192:195], v[128:131]
	v_mfma_f32_16x16x32_bf16 v[124:127], v[140:143], v[192:195], v[124:127]
	v_mfma_f32_16x16x32_bf16 v[112:115], v[132:135], v[200:203], v[112:115]
	v_mfma_f32_16x16x32_bf16 v[108:111], v[140:143], v[200:203], v[108:111]
	v_mfma_f32_16x16x32_bf16 v[96:99], v[132:135], v[218:221], v[96:99]
	v_mfma_f32_16x16x32_bf16 v[92:95], v[140:143], v[218:221], v[92:95]
	v_mfma_f32_16x16x32_bf16 v[80:83], v[132:135], v[226:229], v[80:83]
	v_mfma_f32_16x16x32_bf16 v[76:79], v[140:143], v[226:229], v[76:79]
	v_mfma_f32_16x16x32_bf16 v[128:131], v[136:139], v[196:199], v[128:131]
	v_mfma_f32_16x16x32_bf16 v[124:127], v[144:147], v[196:199], v[124:127]
	v_mfma_f32_16x16x32_bf16 v[112:115], v[136:139], v[204:207], v[112:115]
	v_mfma_f32_16x16x32_bf16 v[108:111], v[144:147], v[204:207], v[108:111]
	v_mfma_f32_16x16x32_bf16 v[96:99], v[136:139], v[222:225], v[96:99]
	v_mfma_f32_16x16x32_bf16 v[92:95], v[144:147], v[222:225], v[92:95]
	v_mfma_f32_16x16x32_bf16 v[80:83], v[136:139], v[230:233], v[80:83]
	v_mfma_f32_16x16x32_bf16 v[76:79], v[144:147], v[230:233], v[76:79]
	v_mfma_f32_16x16x32_bf16 v[120:123], v[148:151], v[192:195], v[120:123]
	v_mfma_f32_16x16x32_bf16 v[116:119], v[184:187], v[192:195], v[116:119]
	v_mfma_f32_16x16x32_bf16 v[104:107], v[148:151], v[200:203], v[104:107]
	v_mfma_f32_16x16x32_bf16 v[100:103], v[184:187], v[200:203], v[100:103]
	v_mfma_f32_16x16x32_bf16 v[88:91], v[148:151], v[218:221], v[88:91]
	v_mfma_f32_16x16x32_bf16 v[84:87], v[184:187], v[218:221], v[84:87]
	v_mfma_f32_16x16x32_bf16 v[72:75], v[148:151], v[226:229], v[72:75]
	v_mfma_f32_16x16x32_bf16 v[68:71], v[184:187], v[226:229], v[68:71]
	v_mfma_f32_16x16x32_bf16 v[120:123], v[152:155], v[196:199], v[120:123]
	v_mfma_f32_16x16x32_bf16 v[116:119], v[188:191], v[196:199], v[116:119]
	v_mfma_f32_16x16x32_bf16 v[104:107], v[152:155], v[204:207], v[104:107]
	v_mfma_f32_16x16x32_bf16 v[100:103], v[188:191], v[204:207], v[100:103]
	v_mfma_f32_16x16x32_bf16 v[88:91], v[152:155], v[222:225], v[88:91]
	v_mfma_f32_16x16x32_bf16 v[84:87], v[188:191], v[222:225], v[84:87]
	v_mfma_f32_16x16x32_bf16 v[72:75], v[152:155], v[230:233], v[72:75]
	v_mfma_f32_16x16x32_bf16 v[68:71], v[188:191], v[230:233], v[68:71]
	s_barrier
; #define PG8_STAGE(bufoff, gbase, voff) do { _Pragma("unroll") for (int _i = 0; _i < 2; ++_i) \
;         __builtin_amdgcn_global_load_lds((const __attribute__((address_space(1))) unsigned*)((const char*)(gbase) + (voff)[_i]), (LAS unsigned*)(lds + (bufoff) + ldsw + _i * 8192), 16, 0, 0); } while (0)
; #define PG8_LDA(dst, b, h) do { _Pragma("unroll") for (int m = 0; m < 4; ++m) _Pragma("unroll") for (int k = 0; k < 2; ++k) dst[m][k] = *(const LAS bf16x8*)(lds + PG8_SA(b, h) + aoff + m * 2048 + k * 1024); } while (0)
; #define PG8_MMA(ai, bj, At, Bt) do { __builtin_amdgcn_s_setprio(1); _Pragma("unroll") for (int m = 0; m < 4; ++m) _Pragma("unroll") for (int n = 0; n < 2; ++n) _Pragma("unroll") for (int k = 0; k < 2; ++k) \
;         acc[ai][bj][m][n] = __builtin_amdgcn_mfma_f32_16x16x32_bf16(Bt[n][k], At[m][k], acc[ai][bj][m][n], 0, 0, 0); __builtin_amdgcn_s_setprio(0); } while (0)
; #define PG8_WAIT_V(n) asm volatile("s_waitcnt vmcnt(" #n ")" ::: "memory")
; #define PG8_WAIT_L(n) asm volatile("s_waitcnt lgkmcnt(" #n ")" ::: "memory")
; #define PG8_BAR __builtin_amdgcn_s_barrier()
; #define PG8_SCHED __builtin_amdgcn_sched_barrier(0)
; template <class Epi, class SchedT, bool ALIGN_EPI, bool SP2>
; __device__ __forceinline__ void gemm_phase(LAS unsigned char* lds, const int ldk, const int nt, const SchedT& S, const Epi& E) {
;     ...
;             PG8_LDA(At, 1, 1); PG8_STAGE(PG8_SB(1, 0), b3, voffB); PG8_STAGE(PG8_SB(1, 1), b3 + hstepB, voffB); PG8_STAGE(PG8_SA(1, 0), a3, voffA);
;             PG8_WAIT_V(8); PG8_WAIT_L(0); PG8_BAR; PG8_MMA(1, 0, At, B0); PG8_MMA(1, 1, At, B1); PG8_BAR; PG8_SCHED;
	s_add_i32 s16, s34, s87
	v_lshl_add_u64 v[6:7], v[208:209], 0, s[24:25]
	s_mov_b32 m0, s16
	ds_read_b128 v[192:195], v216 offset:49152
	ds_read_b128 v[196:199], v216 offset:50176
	ds_read_b128 v[200:203], v216 offset:51200
	ds_read_b128 v[204:207], v216 offset:52224
	ds_read_b128 v[218:221], v216 offset:53248
	ds_read_b128 v[222:225], v216 offset:54272
	ds_read_b128 v[226:229], v216 offset:55296
	ds_read_b128 v[230:233], v216 offset:56320
	global_load_lds_dwordx4 v[6:7], off
	s_add_i32 m0, s16, 0x2000
	s_add_u32 s12, s12, 0x20080
	v_lshl_add_u64 v[6:7], v[234:235], 0, s[24:25]
	s_addc_u32 s13, s13, 0
	s_add_i32 s16, s35, s87
	global_load_lds_dwordx4 v[6:7], off
	v_lshl_add_u64 v[6:7], s[12:13], 0, v[158:159]
	s_mov_b32 m0, s16
	s_nop 0
	global_load_lds_dwordx4 v[6:7], off
	v_lshl_add_u64 v[6:7], s[12:13], 0, v[174:175]
	s_add_i32 m0, s16, 0x2000
	s_nop 0
	global_load_lds_dwordx4 v[6:7], off
	v_lshl_add_u64 v[6:7], v[236:237], 0, s[24:25]
	s_mov_b32 m0, s92
	s_nop 0
	global_load_lds_dwordx4 v[6:7], off
	v_lshl_add_u64 v[6:7], v[238:239], 0, s[24:25]
	s_mov_b32 m0, s93
	s_nop 0
	global_load_lds_dwordx4 v[6:7], off
	s_waitcnt vmcnt(8)
	s_waitcnt lgkmcnt(0)
	s_barrier
	s_waitcnt lgkmcnt(0)
	v_mfma_f32_16x16x32_bf16 v[64:67], v[132:135], v[192:195], v[64:67]
	v_mfma_f32_16x16x32_bf16 v[60:63], v[140:143], v[192:195], v[60:63]
	v_mfma_f32_16x16x32_bf16 v[48:51], v[132:135], v[200:203], v[48:51]
	v_mfma_f32_16x16x32_bf16 v[44:47], v[140:143], v[200:203], v[44:47]
	v_mfma_f32_16x16x32_bf16 v[32:35], v[132:135], v[218:221], v[32:35]
	v_mfma_f32_16x16x32_bf16 v[28:31], v[140:143], v[218:221], v[28:31]
	v_mfma_f32_16x16x32_bf16 v[16:19], v[132:135], v[226:229], v[16:19]
	v_mfma_f32_16x16x32_bf16 v[12:15], v[140:143], v[226:229], v[12:15]
	v_mfma_f32_16x16x32_bf16 v[64:67], v[136:139], v[196:199], v[64:67]
	v_mfma_f32_16x16x32_bf16 v[60:63], v[144:147], v[196:199], v[60:63]
	v_mfma_f32_16x16x32_bf16 v[48:51], v[136:139], v[204:207], v[48:51]
	v_mfma_f32_16x16x32_bf16 v[44:47], v[144:147], v[204:207], v[44:47]
	v_mfma_f32_16x16x32_bf16 v[32:35], v[136:139], v[222:225], v[32:35]
	v_mfma_f32_16x16x32_bf16 v[28:31], v[144:147], v[222:225], v[28:31]
	v_mfma_f32_16x16x32_bf16 v[16:19], v[136:139], v[230:233], v[16:19]
	v_mfma_f32_16x16x32_bf16 v[12:15], v[144:147], v[230:233], v[12:15]
	v_mfma_f32_16x16x32_bf16 v[56:59], v[148:151], v[192:195], v[56:59]
	v_mfma_f32_16x16x32_bf16 v[52:55], v[184:187], v[192:195], v[52:55]
	v_mfma_f32_16x16x32_bf16 v[40:43], v[148:151], v[200:203], v[40:43]
	v_mfma_f32_16x16x32_bf16 v[36:39], v[184:187], v[200:203], v[36:39]
	v_mfma_f32_16x16x32_bf16 v[24:27], v[148:151], v[218:221], v[24:27]
	v_mfma_f32_16x16x32_bf16 v[20:23], v[184:187], v[218:221], v[20:23]
	v_mfma_f32_16x16x32_bf16 v[6:9], v[148:151], v[226:229], v[8:11]
	v_mfma_f32_16x16x32_bf16 v[2:5], v[184:187], v[226:229], v[2:5]
	v_mfma_f32_16x16x32_bf16 v[56:59], v[152:155], v[196:199], v[56:59]
	v_mfma_f32_16x16x32_bf16 v[52:55], v[188:191], v[196:199], v[52:55]
	v_mfma_f32_16x16x32_bf16 v[40:43], v[152:155], v[204:207], v[40:43]
	v_mfma_f32_16x16x32_bf16 v[36:39], v[188:191], v[204:207], v[36:39]
	v_mfma_f32_16x16x32_bf16 v[24:27], v[152:155], v[222:225], v[24:27]
	v_mfma_f32_16x16x32_bf16 v[20:23], v[188:191], v[222:225], v[20:23]
	v_mfma_f32_16x16x32_bf16 v[8:11], v[152:155], v[230:233], v[6:9]
	v_mfma_f32_16x16x32_bf16 v[4:7], v[188:191], v[230:233], v[2:5]
	s_barrier
	s_add_i32 s21, s21, 2
	s_add_u32 s0, s0, 0x100
	s_addc_u32 s1, s1, 0
	s_add_u32 s18, s18, 0x100
	s_addc_u32 s19, s19, 0
	s_cmp_gt_u32 s21, 29

; #define PG8_STAGE(bufoff, gbase, voff) do { _Pragma("unroll") for (int _i = 0; _i < 2; ++_i) \
;         __builtin_amdgcn_global_load_lds((const __attribute__((address_space(1))) unsigned*)((const char*)(gbase) + (voff)[_i]), (LAS unsigned*)(lds + (bufoff) + ldsw + _i * 8192), 16, 0, 0); } while (0)
; #define PG8_LDA(dst, b, h) do { _Pragma("unroll") for (int m = 0; m < 4; ++m) _Pragma("unroll") for (int k = 0; k < 2; ++k) dst[m][k] = *(const LAS bf16x8*)(lds + PG8_SA(b, h) + aoff + m * 2048 + k * 1024); } while (0)
; #define PG8_LDB(dst, b, h) do { _Pragma("unroll") for (int n = 0; n < 2; ++n) _Pragma("unroll") for (int k = 0; k < 2; ++k) dst[n][k] = *(const LAS bf16x8*)(lds + PG8_SB(b, h) + boff + n * 2048 + k * 1024); } while (0)
; #define PG8_MMA(ai, bj, At, Bt) do { __builtin_amdgcn_s_setprio(1); _Pragma("unroll") for (int m = 0; m < 4; ++m) _Pragma("unroll") for (int n = 0; n < 2; ++n) _Pragma("unroll") for (int k = 0; k < 2; ++k) \
;         acc[ai][bj][m][n] = __builtin_amdgcn_mfma_f32_16x16x32_bf16(Bt[n][k], At[m][k], acc[ai][bj][m][n], 0, 0, 0); __builtin_amdgcn_s_setprio(0); } while (0)
; #define PG8_WAIT_V(n) asm volatile("s_waitcnt vmcnt(" #n ")" ::: "memory")
; #define PG8_WAIT_L(n) asm volatile("s_waitcnt lgkmcnt(" #n ")" ::: "memory")
; #define PG8_BAR __builtin_amdgcn_s_barrier()
; #define PG8_SCHED __builtin_amdgcn_sched_barrier(0)
; template <class Epi, class SchedT, bool ALIGN_EPI, bool SP2>
; __device__ __forceinline__ void gemm_phase(LAS unsigned char* lds, const int ldk, const int nt, const SchedT& S, const Epi& E) {
;     ...
;             PG8_LDB(B0, 0, 0); PG8_LDB(B1, 0, 1); PG8_SCHED; PG8_LDA(At, 0, 0); PG8_STAGE(PG8_SA(1, 1), a1 + hstep, voffA);
;             PG8_WAIT_V(8); PG8_WAIT_L(0); PG8_BAR; PG8_MMA(0, 0, At, B0); PG8_MMA(0, 1, At, B1); PG8_BAR; PG8_SCHED;
;             PG8_LDA(At, 0, 1); PG8_STAGE(PG8_SB(0, 0), b2, voffB); PG8_STAGE(PG8_SB(0, 1), b2 + hstepB, voffB); PG8_STAGE(PG8_SA(0, 0), a2, voffA);
;     ...
; #pragma unroll
;         for (int a = 0; a < 2; ++a)
; #pragma unroll
;             for (int b = 0; b < 2; ++b)
; #pragma unroll
;                 for (int m = 0; m < 4; ++m)
; #pragma unroll
;                     for (int n = 0; n < 2; ++n) acc[a][b][m][n] = (f32x4){0.f, 0.f, 0.f, 0.f};
;         }
.LBB0_667:
	s_add_u32 s34, s34, 0x80080
	s_addc_u32 s35, s35, 0
	s_add_u32 s13, s36, 0x100
	s_addc_u32 s20, s37, 0
	s_mov_b32 s22, -2
	s_waitcnt lgkmcnt(0)
	s_add_u32 s36, s34, 0xfff80080
	s_addc_u32 s37, s35, -1
	s_add_i32 s51, 0, 0x10000
	s_cmp_eq_u32 s22, 28
	s_cselect_b32 s57, s1, s37
	s_cselect_b32 s56, s0, s36
	v_add_u32_e32 v144, s51, v147
	s_cselect_b32 s37, s55, s20
	s_cselect_b32 s36, s54, s13
	s_add_i32 s53, 0, 0x14000
	ds_read_b128 v[140:143], v144
	ds_read_b128 v[150:153], v144 offset:1024
	ds_read_b128 v[154:157], v144 offset:2048
	ds_read_b128 v[158:161], v144 offset:3072
	v_add_u32_e32 v144, s53, v147
	ds_read_b128 v[174:177], v144
	ds_read_b128 v[178:181], v144 offset:1024
	ds_read_b128 v[182:185], v144 offset:2048
	ds_read_b128 v[186:189], v144 offset:3072
	v_lshl_add_u64 v[144:145], s[34:35], 0, v[136:137]
	s_add_i32 m0, s17, 0xc000
	ds_read_b128 v[190:193], v149
	ds_read_b128 v[194:197], v149 offset:1024
	ds_read_b128 v[198:201], v149 offset:2048
	ds_read_b128 v[202:205], v149 offset:3072
	ds_read_b128 v[206:209], v149 offset:4096
	ds_read_b128 v[210:213], v149 offset:5120
	ds_read_b128 v[214:217], v149 offset:6144
	ds_read_b128 v[218:221], v149 offset:7168
	global_load_lds_dwordx4 v[144:145], off
	v_lshl_add_u64 v[144:145], s[34:35], 0, v[138:139]
	s_add_i32 m0, s17, 0xe000
	s_nop 0
	global_load_lds_dwordx4 v[144:145], off
	s_waitcnt vmcnt(8)
	s_waitcnt lgkmcnt(0)
	s_barrier
	s_waitcnt lgkmcnt(0)
	v_mfma_f32_16x16x32_bf16 v[126:129], v[140:143], v[190:193], 0
	v_mfma_f32_16x16x32_bf16 v[122:125], v[154:157], v[190:193], 0
	v_mfma_f32_16x16x32_bf16 v[110:113], v[140:143], v[198:201], 0
	v_mfma_f32_16x16x32_bf16 v[106:109], v[154:157], v[198:201], 0
	v_mfma_f32_16x16x32_bf16 v[94:97], v[140:143], v[206:209], 0
	v_mfma_f32_16x16x32_bf16 v[90:93], v[154:157], v[206:209], 0
	v_mfma_f32_16x16x32_bf16 v[78:81], v[140:143], v[214:217], 0
	v_mfma_f32_16x16x32_bf16 v[74:77], v[154:157], v[214:217], 0
	v_mfma_f32_16x16x32_bf16 v[126:129], v[150:153], v[194:197], v[126:129]
	v_mfma_f32_16x16x32_bf16 v[122:125], v[158:161], v[194:197], v[122:125]
	v_mfma_f32_16x16x32_bf16 v[110:113], v[150:153], v[202:205], v[110:113]
	v_mfma_f32_16x16x32_bf16 v[106:109], v[158:161], v[202:205], v[106:109]
	v_mfma_f32_16x16x32_bf16 v[94:97], v[150:153], v[210:213], v[94:97]
	v_mfma_f32_16x16x32_bf16 v[90:93], v[158:161], v[210:213], v[90:93]
	v_mfma_f32_16x16x32_bf16 v[78:81], v[150:153], v[218:221], v[78:81]
	v_mfma_f32_16x16x32_bf16 v[74:77], v[158:161], v[218:221], v[74:77]
	v_mfma_f32_16x16x32_bf16 v[118:121], v[174:177], v[190:193], 0
	v_mfma_f32_16x16x32_bf16 v[114:117], v[182:185], v[190:193], 0
	v_mfma_f32_16x16x32_bf16 v[102:105], v[174:177], v[198:201], 0
	v_mfma_f32_16x16x32_bf16 v[98:101], v[182:185], v[198:201], 0
	v_mfma_f32_16x16x32_bf16 v[86:89], v[174:177], v[206:209], 0
	v_mfma_f32_16x16x32_bf16 v[82:85], v[182:185], v[206:209], 0
	v_mfma_f32_16x16x32_bf16 v[70:73], v[174:177], v[214:217], 0
	v_mfma_f32_16x16x32_bf16 v[66:69], v[182:185], v[214:217], 0
	v_mfma_f32_16x16x32_bf16 v[118:121], v[178:181], v[194:197], v[118:121]
	v_mfma_f32_16x16x32_bf16 v[114:117], v[186:189], v[194:197], v[114:117]
	v_mfma_f32_16x16x32_bf16 v[102:105], v[178:181], v[202:205], v[102:105]
	v_mfma_f32_16x16x32_bf16 v[98:101], v[186:189], v[202:205], v[98:101]
	v_mfma_f32_16x16x32_bf16 v[86:89], v[178:181], v[210:213], v[86:89]
	v_mfma_f32_16x16x32_bf16 v[82:85], v[186:189], v[210:213], v[82:85]
	v_mfma_f32_16x16x32_bf16 v[70:73], v[178:181], v[218:221], v[70:73]
	v_mfma_f32_16x16x32_bf16 v[66:69], v[186:189], v[218:221], v[66:69]
	s_barrier
	s_add_i32 s51, s51, s61
	v_lshl_add_u64 v[144:145], s[36:37], 0, v[0:1]
	s_mov_b32 m0, s51
	ds_read_b128 v[190:193], v149 offset:16384
	ds_read_b128 v[194:197], v149 offset:17408
	ds_read_b128 v[198:201], v149 offset:18432
	ds_read_b128 v[202:205], v149 offset:19456
	ds_read_b128 v[206:209], v149 offset:20480
	ds_read_b128 v[210:213], v149 offset:21504
	ds_read_b128 v[214:217], v149 offset:22528
	ds_read_b128 v[218:221], v149 offset:23552
	global_load_lds_dwordx4 v[144:145], off
	s_add_i32 m0, s51, 0x2000
	s_add_u32 s86, s36, 0x20000
	v_lshl_add_u64 v[222:223], s[36:37], 0, v[134:135]
	s_addc_u32 s87, s37, 0
	s_add_i32 s51, s53, s61
	global_load_lds_dwordx4 v[222:223], off
	v_lshl_add_u64 v[224:225], s[86:87], 0, v[0:1]
	s_mov_b32 m0, s51
	v_lshl_add_u64 v[226:227], s[56:57], 0, v[132:133]
	global_load_lds_dwordx4 v[224:225], off
	v_lshl_add_u64 v[224:225], s[86:87], 0, v[134:135]
	s_add_i32 m0, s51, 0x2000
	s_nop 0
	global_load_lds_dwordx4 v[224:225], off
	v_lshl_add_u64 v[224:225], s[56:57], 0, v[130:131]
	s_mov_b32 m0, s17
	s_nop 0
	global_load_lds_dwordx4 v[224:225], off
	s_mov_b32 m0, s62
	s_nop 0
	global_load_lds_dwordx4 v[226:227], off
	s_waitcnt vmcnt(8)
	s_waitcnt lgkmcnt(0)
	s_barrier
; #define PG8_STAGE(bufoff, gbase, voff) do { _Pragma("unroll") for (int _i = 0; _i < 2; ++_i) \
;         __builtin_amdgcn_global_load_lds((const __attribute__((address_space(1))) unsigned*)((const char*)(gbase) + (voff)[_i]), (LAS unsigned*)(lds + (bufoff) + ldsw + _i * 8192), 16, 0, 0); } while (0)
; #define PG8_LDA(dst, b, h) do { _Pragma("unroll") for (int m = 0; m < 4; ++m) _Pragma("unroll") for (int k = 0; k < 2; ++k) dst[m][k] = *(const LAS bf16x8*)(lds + PG8_SA(b, h) + aoff + m * 2048 + k * 1024); } while (0)
; #define PG8_LDB(dst, b, h) do { _Pragma("unroll") for (int n = 0; n < 2; ++n) _Pragma("unroll") for (int k = 0; k < 2; ++k) dst[n][k] = *(const LAS bf16x8*)(lds + PG8_SB(b, h) + boff + n * 2048 + k * 1024); } while (0)
; #define PG8_MMA(ai, bj, At, Bt) do { __builtin_amdgcn_s_setprio(1); _Pragma("unroll") for (int m = 0; m < 4; ++m) _Pragma("unroll") for (int n = 0; n < 2; ++n) _Pragma("unroll") for (int k = 0; k < 2; ++k) \
;         acc[ai][bj][m][n] = __builtin_amdgcn_mfma_f32_16x16x32_bf16(Bt[n][k], At[m][k], acc[ai][bj][m][n], 0, 0, 0); __builtin_amdgcn_s_setprio(0); } while (0)
; #define PG8_WAIT_V(n) asm volatile("s_waitcnt vmcnt(" #n ")" ::: "memory")
; #define PG8_WAIT_L(n) asm volatile("s_waitcnt lgkmcnt(" #n ")" ::: "memory")
; #define PG8_BAR __builtin_amdgcn_s_barrier()
; #define PG8_SCHED __builtin_amdgcn_sched_barrier(0)
; template <class Epi, class SchedT, bool ALIGN_EPI, bool SP2>
; __device__ __forceinline__ void gemm_phase(LAS unsigned char* lds, const int ldk, const int nt, const SchedT& S, const Epi& E) {
;     ...
;             PG8_WAIT_V(8); PG8_WAIT_L(0); PG8_BAR; PG8_MMA(1, 0, At, B0); PG8_MMA(1, 1, At, B1); PG8_BAR; PG8_SCHED;
;             PG8_LDB(B0, 1, 0); PG8_LDB(B1, 1, 1); PG8_SCHED; PG8_LDA(At, 1, 0); PG8_STAGE(PG8_SA(0, 1), a2 + hstep, voffA);
;             PG8_WAIT_V(8); PG8_WAIT_L(0); PG8_BAR; PG8_MMA(0, 0, At, B0); PG8_MMA(0, 1, At, B1); PG8_BAR; PG8_SCHED;
	s_waitcnt lgkmcnt(0)
	v_mfma_f32_16x16x32_bf16 v[62:65], v[140:143], v[190:193], 0
	v_mfma_f32_16x16x32_bf16 v[58:61], v[154:157], v[190:193], 0
	v_mfma_f32_16x16x32_bf16 v[46:49], v[140:143], v[198:201], 0
	v_mfma_f32_16x16x32_bf16 v[42:45], v[154:157], v[198:201], 0
	v_mfma_f32_16x16x32_bf16 v[30:33], v[140:143], v[206:209], 0
	v_mfma_f32_16x16x32_bf16 v[26:29], v[154:157], v[206:209], 0
	v_mfma_f32_16x16x32_bf16 v[14:17], v[140:143], v[214:217], 0
	v_mfma_f32_16x16x32_bf16 v[10:13], v[154:157], v[214:217], 0
	v_mfma_f32_16x16x32_bf16 v[62:65], v[150:153], v[194:197], v[62:65]
	v_mfma_f32_16x16x32_bf16 v[58:61], v[158:161], v[194:197], v[58:61]
	v_mfma_f32_16x16x32_bf16 v[46:49], v[150:153], v[202:205], v[46:49]
	v_mfma_f32_16x16x32_bf16 v[42:45], v[158:161], v[202:205], v[42:45]
	v_mfma_f32_16x16x32_bf16 v[30:33], v[150:153], v[210:213], v[30:33]
	v_mfma_f32_16x16x32_bf16 v[26:29], v[158:161], v[210:213], v[26:29]
	v_mfma_f32_16x16x32_bf16 v[14:17], v[150:153], v[218:221], v[14:17]
	v_mfma_f32_16x16x32_bf16 v[10:13], v[158:161], v[218:221], v[10:13]
	v_mfma_f32_16x16x32_bf16 v[54:57], v[174:177], v[190:193], 0
	v_mfma_f32_16x16x32_bf16 v[50:53], v[182:185], v[190:193], 0
	v_mfma_f32_16x16x32_bf16 v[38:41], v[174:177], v[198:201], 0
	v_mfma_f32_16x16x32_bf16 v[34:37], v[182:185], v[198:201], 0
	v_mfma_f32_16x16x32_bf16 v[22:25], v[174:177], v[206:209], 0
	v_mfma_f32_16x16x32_bf16 v[18:21], v[182:185], v[206:209], 0
	v_mfma_f32_16x16x32_bf16 v[6:9], v[174:177], v[214:217], 0
	v_mfma_f32_16x16x32_bf16 v[2:5], v[182:185], v[214:217], 0
	v_mfma_f32_16x16x32_bf16 v[54:57], v[178:181], v[194:197], v[54:57]
	v_mfma_f32_16x16x32_bf16 v[50:53], v[186:189], v[194:197], v[50:53]
	v_mfma_f32_16x16x32_bf16 v[38:41], v[178:181], v[202:205], v[38:41]
	v_mfma_f32_16x16x32_bf16 v[34:37], v[186:189], v[202:205], v[34:37]
	v_mfma_f32_16x16x32_bf16 v[22:25], v[178:181], v[210:213], v[22:25]
	v_mfma_f32_16x16x32_bf16 v[18:21], v[186:189], v[210:213], v[18:21]
	v_mfma_f32_16x16x32_bf16 v[6:9], v[178:181], v[218:221], v[6:9]
	v_mfma_f32_16x16x32_bf16 v[2:5], v[186:189], v[218:221], v[2:5]
	s_barrier
	s_add_i32 s51, 0, 0x18000
	s_add_i32 s53, 0, 0x1c000
	v_add_u32_e32 v158, s51, v147
	v_add_u32_e32 v186, s53, v147
	ds_read_b128 v[140:143], v158
	ds_read_b128 v[150:153], v158 offset:1024
	ds_read_b128 v[154:157], v158 offset:2048
	ds_read_b128 v[158:161], v158 offset:3072
	ds_read_b128 v[174:177], v186
	ds_read_b128 v[178:181], v186 offset:1024
	ds_read_b128 v[182:185], v186 offset:2048
	ds_read_b128 v[186:189], v186 offset:3072
	s_add_u32 s56, s56, 0x80000
	s_addc_u32 s57, s57, 0
	s_mov_b32 m0, s63
	v_lshl_add_u64 v[228:229], s[56:57], 0, v[130:131]
	ds_read_b128 v[190:193], v149 offset:32768
	ds_read_b128 v[194:197], v149 offset:33792
	ds_read_b128 v[198:201], v149 offset:34816
	ds_read_b128 v[202:205], v149 offset:35840
	ds_read_b128 v[206:209], v149 offset:36864
	ds_read_b128 v[210:213], v149 offset:37888
	ds_read_b128 v[214:217], v149 offset:38912
	ds_read_b128 v[218:221], v149 offset:39936
	global_load_lds_dwordx4 v[228:229], off
	v_lshl_add_u64 v[228:229], s[56:57], 0, v[132:133]
	s_mov_b32 m0, s81
	s_nop 0
	global_load_lds_dwordx4 v[228:229], off
	s_waitcnt vmcnt(8)
	s_waitcnt lgkmcnt(0)
	s_barrier
	s_waitcnt lgkmcnt(0)
	v_mfma_f32_16x16x32_bf16 v[126:129], v[140:143], v[190:193], v[126:129]
	v_mfma_f32_16x16x32_bf16 v[122:125], v[154:157], v[190:193], v[122:125]
	v_mfma_f32_16x16x32_bf16 v[110:113], v[140:143], v[198:201], v[110:113]
	v_mfma_f32_16x16x32_bf16 v[106:109], v[154:157], v[198:201], v[106:109]
	v_mfma_f32_16x16x32_bf16 v[94:97], v[140:143], v[206:209], v[94:97]
	v_mfma_f32_16x16x32_bf16 v[90:93], v[154:157], v[206:209], v[90:93]
	v_mfma_f32_16x16x32_bf16 v[78:81], v[140:143], v[214:217], v[78:81]
	v_mfma_f32_16x16x32_bf16 v[74:77], v[154:157], v[214:217], v[74:77]
	v_mfma_f32_16x16x32_bf16 v[126:129], v[150:153], v[194:197], v[126:129]
	v_mfma_f32_16x16x32_bf16 v[122:125], v[158:161], v[194:197], v[122:125]
	v_mfma_f32_16x16x32_bf16 v[110:113], v[150:153], v[202:205], v[110:113]
	v_mfma_f32_16x16x32_bf16 v[106:109], v[158:161], v[202:205], v[106:109]
	v_mfma_f32_16x16x32_bf16 v[94:97], v[150:153], v[210:213], v[94:97]
	v_mfma_f32_16x16x32_bf16 v[90:93], v[158:161], v[210:213], v[90:93]
	v_mfma_f32_16x16x32_bf16 v[78:81], v[150:153], v[218:221], v[78:81]
	v_mfma_f32_16x16x32_bf16 v[74:77], v[158:161], v[218:221], v[74:77]
	v_mfma_f32_16x16x32_bf16 v[118:121], v[174:177], v[190:193], v[118:121]
	v_mfma_f32_16x16x32_bf16 v[114:117], v[182:185], v[190:193], v[114:117]
	v_mfma_f32_16x16x32_bf16 v[102:105], v[174:177], v[198:201], v[102:105]
	v_mfma_f32_16x16x32_bf16 v[98:101], v[182:185], v[198:201], v[98:101]
	v_mfma_f32_16x16x32_bf16 v[86:89], v[174:177], v[206:209], v[86:89]
	v_mfma_f32_16x16x32_bf16 v[82:85], v[182:185], v[206:209], v[82:85]
	v_mfma_f32_16x16x32_bf16 v[70:73], v[174:177], v[214:217], v[70:73]
	v_mfma_f32_16x16x32_bf16 v[66:69], v[182:185], v[214:217], v[66:69]
	v_mfma_f32_16x16x32_bf16 v[118:121], v[178:181], v[194:197], v[118:121]
	v_mfma_f32_16x16x32_bf16 v[114:117], v[186:189], v[194:197], v[114:117]
	v_mfma_f32_16x16x32_bf16 v[102:105], v[178:181], v[202:205], v[102:105]
	v_mfma_f32_16x16x32_bf16 v[98:101], v[186:189], v[202:205], v[98:101]
	v_mfma_f32_16x16x32_bf16 v[86:89], v[178:181], v[210:213], v[86:89]
	v_mfma_f32_16x16x32_bf16 v[82:85], v[186:189], v[210:213], v[82:85]
	v_mfma_f32_16x16x32_bf16 v[70:73], v[178:181], v[218:221], v[70:73]
	v_mfma_f32_16x16x32_bf16 v[66:69], v[186:189], v[218:221], v[66:69]
	s_barrier
; #define PG8_STAGE(bufoff, gbase, voff) do { _Pragma("unroll") for (int _i = 0; _i < 2; ++_i) \
;         __builtin_amdgcn_global_load_lds((const __attribute__((address_space(1))) unsigned*)((const char*)(gbase) + (voff)[_i]), (LAS unsigned*)(lds + (bufoff) + ldsw + _i * 8192), 16, 0, 0); } while (0)
; #define PG8_LDA(dst, b, h) do { _Pragma("unroll") for (int m = 0; m < 4; ++m) _Pragma("unroll") for (int k = 0; k < 2; ++k) dst[m][k] = *(const LAS bf16x8*)(lds + PG8_SA(b, h) + aoff + m * 2048 + k * 1024); } while (0)
; #define PG8_MMA(ai, bj, At, Bt) do { __builtin_amdgcn_s_setprio(1); _Pragma("unroll") for (int m = 0; m < 4; ++m) _Pragma("unroll") for (int n = 0; n < 2; ++n) _Pragma("unroll") for (int k = 0; k < 2; ++k) \
;         acc[ai][bj][m][n] = __builtin_amdgcn_mfma_f32_16x16x32_bf16(Bt[n][k], At[m][k], acc[ai][bj][m][n], 0, 0, 0); __builtin_amdgcn_s_setprio(0); } while (0)
; #define PG8_WAIT_V(n) asm volatile("s_waitcnt vmcnt(" #n ")" ::: "memory")
; #define PG8_WAIT_L(n) asm volatile("s_waitcnt lgkmcnt(" #n ")" ::: "memory")
; #define PG8_BAR __builtin_amdgcn_s_barrier()
; #define PG8_SCHED __builtin_amdgcn_sched_barrier(0)
; template <class Epi, class SchedT, bool ALIGN_EPI, bool SP2>
; __device__ __forceinline__ void gemm_phase(LAS unsigned char* lds, const int ldk, const int nt, const SchedT& S, const Epi& E) {
;     ...
;             PG8_LDA(At, 1, 1); PG8_STAGE(PG8_SB(1, 0), b3, voffB); PG8_STAGE(PG8_SB(1, 1), b3 + hstepB, voffB); PG8_STAGE(PG8_SA(1, 0), a3, voffA);
;             PG8_WAIT_V(8); PG8_WAIT_L(0); PG8_BAR; PG8_MMA(1, 0, At, B0); PG8_MMA(1, 1, At, B1); PG8_BAR; PG8_SCHED;
	s_add_i32 s51, s51, s61
	v_lshl_add_u64 v[144:145], v[144:145], 0, s[24:25]
	s_mov_b32 m0, s51
	ds_read_b128 v[190:193], v149 offset:49152
	ds_read_b128 v[194:197], v149 offset:50176
	ds_read_b128 v[198:201], v149 offset:51200
	ds_read_b128 v[202:205], v149 offset:52224
	ds_read_b128 v[206:209], v149 offset:53248
	ds_read_b128 v[210:213], v149 offset:54272
	ds_read_b128 v[214:217], v149 offset:55296
	ds_read_b128 v[218:221], v149 offset:56320
	global_load_lds_dwordx4 v[144:145], off
	s_add_i32 m0, s51, 0x2000
	s_add_u32 s36, s36, 0x20080
	v_lshl_add_u64 v[144:145], v[222:223], 0, s[24:25]
	s_addc_u32 s37, s37, 0
	s_add_i32 s51, s53, s61
	global_load_lds_dwordx4 v[144:145], off
	v_lshl_add_u64 v[144:145], s[36:37], 0, v[0:1]
	s_mov_b32 m0, s51
	s_nop 0
	global_load_lds_dwordx4 v[144:145], off
	v_lshl_add_u64 v[144:145], s[36:37], 0, v[134:135]
	s_add_i32 m0, s51, 0x2000
	s_nop 0
	global_load_lds_dwordx4 v[144:145], off
	v_lshl_add_u64 v[144:145], v[224:225], 0, s[24:25]
	s_mov_b32 m0, s83
	s_nop 0
	global_load_lds_dwordx4 v[144:145], off
	v_lshl_add_u64 v[144:145], v[226:227], 0, s[24:25]
	s_mov_b32 m0, s84
	s_nop 0
	global_load_lds_dwordx4 v[144:145], off
	s_waitcnt vmcnt(8)
	s_waitcnt lgkmcnt(0)
	s_barrier
	s_waitcnt lgkmcnt(0)
	v_mfma_f32_16x16x32_bf16 v[62:65], v[140:143], v[190:193], v[62:65]
	v_mfma_f32_16x16x32_bf16 v[58:61], v[154:157], v[190:193], v[58:61]
	v_mfma_f32_16x16x32_bf16 v[46:49], v[140:143], v[198:201], v[46:49]
	v_mfma_f32_16x16x32_bf16 v[42:45], v[154:157], v[198:201], v[42:45]
	v_mfma_f32_16x16x32_bf16 v[30:33], v[140:143], v[206:209], v[30:33]
	v_mfma_f32_16x16x32_bf16 v[26:29], v[154:157], v[206:209], v[26:29]
	v_mfma_f32_16x16x32_bf16 v[14:17], v[140:143], v[214:217], v[14:17]
	v_mfma_f32_16x16x32_bf16 v[10:13], v[154:157], v[214:217], v[10:13]
	v_mfma_f32_16x16x32_bf16 v[62:65], v[150:153], v[194:197], v[62:65]
	v_mfma_f32_16x16x32_bf16 v[58:61], v[158:161], v[194:197], v[58:61]
	v_mfma_f32_16x16x32_bf16 v[46:49], v[150:153], v[202:205], v[46:49]
	v_mfma_f32_16x16x32_bf16 v[42:45], v[158:161], v[202:205], v[42:45]
	v_mfma_f32_16x16x32_bf16 v[30:33], v[150:153], v[210:213], v[30:33]
	v_mfma_f32_16x16x32_bf16 v[26:29], v[158:161], v[210:213], v[26:29]
	v_mfma_f32_16x16x32_bf16 v[14:17], v[150:153], v[218:221], v[14:17]
	v_mfma_f32_16x16x32_bf16 v[10:13], v[158:161], v[218:221], v[10:13]
	v_mfma_f32_16x16x32_bf16 v[54:57], v[174:177], v[190:193], v[54:57]
	v_mfma_f32_16x16x32_bf16 v[50:53], v[182:185], v[190:193], v[50:53]
	v_mfma_f32_16x16x32_bf16 v[38:41], v[174:177], v[198:201], v[38:41]
	v_mfma_f32_16x16x32_bf16 v[34:37], v[182:185], v[198:201], v[34:37]
	v_mfma_f32_16x16x32_bf16 v[22:25], v[174:177], v[206:209], v[22:25]
	v_mfma_f32_16x16x32_bf16 v[18:21], v[182:185], v[206:209], v[18:21]
	v_mfma_f32_16x16x32_bf16 v[6:9], v[174:177], v[214:217], v[6:9]
	v_mfma_f32_16x16x32_bf16 v[2:5], v[182:185], v[214:217], v[2:5]
	v_mfma_f32_16x16x32_bf16 v[54:57], v[178:181], v[194:197], v[54:57]
	v_mfma_f32_16x16x32_bf16 v[50:53], v[186:189], v[194:197], v[50:53]
	v_mfma_f32_16x16x32_bf16 v[38:41], v[178:181], v[202:205], v[38:41]
	v_mfma_f32_16x16x32_bf16 v[34:37], v[186:189], v[202:205], v[34:37]
	v_mfma_f32_16x16x32_bf16 v[22:25], v[178:181], v[210:213], v[22:25]
	v_mfma_f32_16x16x32_bf16 v[18:21], v[186:189], v[210:213], v[18:21]
	v_mfma_f32_16x16x32_bf16 v[6:9], v[178:181], v[218:221], v[6:9]
	v_mfma_f32_16x16x32_bf16 v[2:5], v[186:189], v[218:221], v[2:5]
	s_barrier
	s_add_i32 s22, s22, 2
	s_add_u32 s34, s34, 0x100
	s_addc_u32 s35, s35, 0
	s_add_u32 s13, s13, 0x100
	s_addc_u32 s20, s20, 0
	s_cmp_gt_u32 s22, 29

; #define PG8_STAGE(bufoff, gbase, voff) do { _Pragma("unroll") for (int _i = 0; _i < 2; ++_i) \
;         __builtin_amdgcn_global_load_lds((const __attribute__((address_space(1))) unsigned*)((const char*)(gbase) + (voff)[_i]), (LAS unsigned*)(lds + (bufoff) + ldsw + _i * 8192), 16, 0, 0); } while (0)
; #define PG8_LDA(dst, b, h) do { _Pragma("unroll") for (int m = 0; m < 4; ++m) _Pragma("unroll") for (int k = 0; k < 2; ++k) dst[m][k] = *(const LAS bf16x8*)(lds + PG8_SA(b, h) + aoff + m * 2048 + k * 1024); } while (0)
; #define PG8_LDB(dst, b, h) do { _Pragma("unroll") for (int n = 0; n < 2; ++n) _Pragma("unroll") for (int k = 0; k < 2; ++k) dst[n][k] = *(const LAS bf16x8*)(lds + PG8_SB(b, h) + boff + n * 2048 + k * 1024); } while (0)
; #define PG8_MMA(ai, bj, At, Bt) do { __builtin_amdgcn_s_setprio(1); _Pragma("unroll") for (int m = 0; m < 4; ++m) _Pragma("unroll") for (int n = 0; n < 2; ++n) _Pragma("unroll") for (int k = 0; k < 2; ++k) \
;         acc[ai][bj][m][n] = __builtin_amdgcn_mfma_f32_16x16x32_bf16(Bt[n][k], At[m][k], acc[ai][bj][m][n], 0, 0, 0); __builtin_amdgcn_s_setprio(0); } while (0)
; #define PG8_WAIT_V(n) asm volatile("s_waitcnt vmcnt(" #n ")" ::: "memory")
; #define PG8_WAIT_L(n) asm volatile("s_waitcnt lgkmcnt(" #n ")" ::: "memory")
; #define PG8_BAR __builtin_amdgcn_s_barrier()
; #define PG8_SCHED __builtin_amdgcn_sched_barrier(0)
; template <class Epi, class SchedT, bool ALIGN_EPI, bool SP2>
; __device__ __forceinline__ void gemm_phase(LAS unsigned char* lds, const int ldk, const int nt, const SchedT& S, const Epi& E) {
;     ...
;             PG8_LDB(B0, 0, 0); PG8_LDB(B1, 0, 1); PG8_SCHED; PG8_LDA(At, 0, 0); PG8_STAGE(PG8_SA(1, 1), a1 + hstep, voffA);
;             PG8_WAIT_V(8); PG8_WAIT_L(0); PG8_BAR; PG8_MMA(0, 0, At, B0); PG8_MMA(0, 1, At, B1); PG8_BAR; PG8_SCHED;
;             PG8_LDA(At, 0, 1); PG8_STAGE(PG8_SB(0, 0), b2, voffB); PG8_STAGE(PG8_SB(0, 1), b2 + hstepB, voffB); PG8_STAGE(PG8_SA(0, 0), a2, voffA);
;     ...
; #pragma unroll
;         for (int a = 0; a < 2; ++a)
; #pragma unroll
;             for (int b = 0; b < 2; ++b)
; #pragma unroll
;                 for (int m = 0; m < 4; ++m)
; #pragma unroll
;                     for (int n = 0; n < 2; ++n) acc[a][b][m][n] = (f32x4){0.f, 0.f, 0.f, 0.f};
;         }
.LBB0_751:
	s_add_u32 s34, s34, 0x80080
	s_addc_u32 s35, s35, 0
	s_add_u32 s13, s36, 0x100
	s_addc_u32 s17, s37, 0
	s_mov_b32 s59, -2
	s_add_u32 s36, s34, 0xfff80080
	s_addc_u32 s37, s35, -1
	s_add_i32 s61, 0, 0x10000
	s_cmp_eq_u32 s59, 28
	s_cselect_b32 vcc_hi, s1, s37
	s_cselect_b32 vcc_lo, s0, s36
	s_cselect_b32 s37, s63, s17
	s_cselect_b32 s36, s62, s13
	s_add_i32 s64, 0, 0x14000
	v_add_u32_e32 v142, s61, v248
	v_add_u32_e32 v182, s64, v248
	ds_read_b128 v[130:133], v142
	ds_read_b128 v[134:137], v142 offset:1024
	ds_read_b128 v[138:141], v142 offset:2048
	ds_read_b128 v[142:145], v142 offset:3072
	ds_read_b128 v[158:161], v182
	ds_read_b128 v[174:177], v182 offset:1024
	ds_read_b128 v[178:181], v182 offset:2048
	ds_read_b128 v[182:185], v182 offset:3072
	v_lshl_add_u64 v[218:219], s[34:35], 0, v[154:155]
	s_add_i32 m0, s85, 0xc000
	ds_read_b128 v[186:189], v251
	ds_read_b128 v[190:193], v251 offset:1024
	ds_read_b128 v[194:197], v251 offset:2048
	ds_read_b128 v[198:201], v251 offset:3072
	ds_read_b128 v[202:205], v251 offset:4096
	ds_read_b128 v[206:209], v251 offset:5120
	ds_read_b128 v[210:213], v251 offset:6144
	ds_read_b128 v[214:217], v251 offset:7168
	global_load_lds_dwordx4 v[218:219], off
	v_lshl_add_u64 v[218:219], s[34:35], 0, v[156:157]
	s_add_i32 m0, s85, 0xe000
	s_nop 0
	global_load_lds_dwordx4 v[218:219], off
	s_waitcnt vmcnt(8)
	s_waitcnt lgkmcnt(0)
	s_barrier
	s_waitcnt lgkmcnt(0)
	v_mfma_f32_16x16x32_bf16 v[126:129], v[130:133], v[186:189], 0
	v_mfma_f32_16x16x32_bf16 v[62:65], v[138:141], v[186:189], 0
	v_mfma_f32_16x16x32_bf16 v[118:121], v[130:133], v[194:197], 0
	v_mfma_f32_16x16x32_bf16 v[58:61], v[138:141], v[194:197], 0
	v_mfma_f32_16x16x32_bf16 v[110:113], v[130:133], v[202:205], 0
	v_mfma_f32_16x16x32_bf16 v[46:49], v[138:141], v[202:205], 0
	v_mfma_f32_16x16x32_bf16 v[106:109], v[130:133], v[210:213], 0
	v_mfma_f32_16x16x32_bf16 v[42:45], v[138:141], v[210:213], 0
	v_mfma_f32_16x16x32_bf16 v[126:129], v[134:137], v[190:193], v[126:129]
	v_mfma_f32_16x16x32_bf16 v[62:65], v[142:145], v[190:193], v[62:65]
	v_mfma_f32_16x16x32_bf16 v[118:121], v[134:137], v[198:201], v[118:121]
	v_mfma_f32_16x16x32_bf16 v[58:61], v[142:145], v[198:201], v[58:61]
	v_mfma_f32_16x16x32_bf16 v[110:113], v[134:137], v[206:209], v[110:113]
	v_mfma_f32_16x16x32_bf16 v[46:49], v[142:145], v[206:209], v[46:49]
	v_mfma_f32_16x16x32_bf16 v[106:109], v[134:137], v[214:217], v[106:109]
	v_mfma_f32_16x16x32_bf16 v[42:45], v[142:145], v[214:217], v[42:45]
	v_mfma_f32_16x16x32_bf16 v[122:125], v[158:161], v[186:189], 0
	v_mfma_f32_16x16x32_bf16 v[54:57], v[178:181], v[186:189], 0
	v_mfma_f32_16x16x32_bf16 v[114:117], v[158:161], v[194:197], 0
	v_mfma_f32_16x16x32_bf16 v[50:53], v[178:181], v[194:197], 0
	v_mfma_f32_16x16x32_bf16 v[102:105], v[158:161], v[202:205], 0
	v_mfma_f32_16x16x32_bf16 v[38:41], v[178:181], v[202:205], 0
	v_mfma_f32_16x16x32_bf16 v[98:101], v[158:161], v[210:213], 0
	v_mfma_f32_16x16x32_bf16 v[34:37], v[178:181], v[210:213], 0
	v_mfma_f32_16x16x32_bf16 v[122:125], v[174:177], v[190:193], v[122:125]
	v_mfma_f32_16x16x32_bf16 v[54:57], v[182:185], v[190:193], v[54:57]
	v_mfma_f32_16x16x32_bf16 v[114:117], v[174:177], v[198:201], v[114:117]
	v_mfma_f32_16x16x32_bf16 v[50:53], v[182:185], v[198:201], v[50:53]
	v_mfma_f32_16x16x32_bf16 v[102:105], v[174:177], v[206:209], v[102:105]
	v_mfma_f32_16x16x32_bf16 v[38:41], v[182:185], v[206:209], v[38:41]
	v_mfma_f32_16x16x32_bf16 v[98:101], v[174:177], v[214:217], v[98:101]
	v_mfma_f32_16x16x32_bf16 v[34:37], v[182:185], v[214:217], v[34:37]
	s_barrier
	s_add_i32 s61, s61, s84
	v_lshl_add_u64 v[218:219], s[36:37], 0, v[0:1]
	s_mov_b32 m0, s61
	ds_read_b128 v[186:189], v251 offset:16384
	ds_read_b128 v[190:193], v251 offset:17408
	ds_read_b128 v[194:197], v251 offset:18432
	ds_read_b128 v[198:201], v251 offset:19456
	ds_read_b128 v[202:205], v251 offset:20480
	ds_read_b128 v[206:209], v251 offset:21504
	ds_read_b128 v[210:213], v251 offset:22528
	ds_read_b128 v[214:217], v251 offset:23552
	global_load_lds_dwordx4 v[218:219], off
	s_add_i32 m0, s61, 0x2000
	s_add_u32 s94, s36, 0x20000
	v_lshl_add_u64 v[220:221], s[36:37], 0, v[150:151]
	s_addc_u32 s95, s37, 0
	s_add_i32 s61, s64, s84
	global_load_lds_dwordx4 v[220:221], off
	v_lshl_add_u64 v[222:223], s[94:95], 0, v[0:1]
	s_mov_b32 m0, s61
	v_lshl_add_u64 v[224:225], vcc, 0, v[148:149]
	global_load_lds_dwordx4 v[222:223], off
	v_lshl_add_u64 v[222:223], s[94:95], 0, v[150:151]
	s_add_i32 m0, s61, 0x2000
	s_nop 0
	global_load_lds_dwordx4 v[222:223], off
	v_lshl_add_u64 v[222:223], vcc, 0, v[146:147]
	s_mov_b32 m0, s85
	s_nop 0
	global_load_lds_dwordx4 v[222:223], off
	s_mov_b32 m0, s86
	s_nop 0
	global_load_lds_dwordx4 v[224:225], off
	s_waitcnt vmcnt(8)
	s_waitcnt lgkmcnt(0)
	s_barrier
; #define PG8_STAGE(bufoff, gbase, voff) do { _Pragma("unroll") for (int _i = 0; _i < 2; ++_i) \
;         __builtin_amdgcn_global_load_lds((const __attribute__((address_space(1))) unsigned*)((const char*)(gbase) + (voff)[_i]), (LAS unsigned*)(lds + (bufoff) + ldsw + _i * 8192), 16, 0, 0); } while (0)
; #define PG8_LDA(dst, b, h) do { _Pragma("unroll") for (int m = 0; m < 4; ++m) _Pragma("unroll") for (int k = 0; k < 2; ++k) dst[m][k] = *(const LAS bf16x8*)(lds + PG8_SA(b, h) + aoff + m * 2048 + k * 1024); } while (0)
; #define PG8_LDB(dst, b, h) do { _Pragma("unroll") for (int n = 0; n < 2; ++n) _Pragma("unroll") for (int k = 0; k < 2; ++k) dst[n][k] = *(const LAS bf16x8*)(lds + PG8_SB(b, h) + boff + n * 2048 + k * 1024); } while (0)
; #define PG8_MMA(ai, bj, At, Bt) do { __builtin_amdgcn_s_setprio(1); _Pragma("unroll") for (int m = 0; m < 4; ++m) _Pragma("unroll") for (int n = 0; n < 2; ++n) _Pragma("unroll") for (int k = 0; k < 2; ++k) \
;         acc[ai][bj][m][n] = __builtin_amdgcn_mfma_f32_16x16x32_bf16(Bt[n][k], At[m][k], acc[ai][bj][m][n], 0, 0, 0); __builtin_amdgcn_s_setprio(0); } while (0)
; #define PG8_WAIT_V(n) asm volatile("s_waitcnt vmcnt(" #n ")" ::: "memory")
; #define PG8_WAIT_L(n) asm volatile("s_waitcnt lgkmcnt(" #n ")" ::: "memory")
; #define PG8_BAR __builtin_amdgcn_s_barrier()
; #define PG8_SCHED __builtin_amdgcn_sched_barrier(0)
; template <class Epi, class SchedT, bool ALIGN_EPI, bool SP2>
; __device__ __forceinline__ void gemm_phase(LAS unsigned char* lds, const int ldk, const int nt, const SchedT& S, const Epi& E) {
;     ...
;             PG8_LDB(B0, 0, 0); PG8_LDB(B1, 0, 1); PG8_SCHED; PG8_LDA(At, 0, 0); PG8_STAGE(PG8_SA(1, 1), a1 + hstep, voffA);
;             PG8_WAIT_V(8); PG8_WAIT_L(0); PG8_BAR; PG8_MMA(0, 0, At, B0); PG8_MMA(0, 1, At, B1); PG8_BAR; PG8_SCHED;
;             PG8_LDA(At, 0, 1); PG8_STAGE(PG8_SB(0, 0), b2, voffB); PG8_STAGE(PG8_SB(0, 1), b2 + hstepB, voffB); PG8_STAGE(PG8_SA(0, 0), a2, voffA);
;             PG8_WAIT_V(8); PG8_WAIT_L(0); PG8_BAR; PG8_MMA(1, 0, At, B0); PG8_MMA(1, 1, At, B1); PG8_BAR; PG8_SCHED;
;             PG8_LDB(B0, 1, 0); PG8_LDB(B1, 1, 1); PG8_SCHED; PG8_LDA(At, 1, 0); PG8_STAGE(PG8_SA(0, 1), a2 + hstep, voffA);
;             PG8_WAIT_V(8); PG8_WAIT_L(0); PG8_BAR; PG8_MMA(0, 0, At, B0); PG8_MMA(0, 1, At, B1); PG8_BAR; PG8_SCHED;
	s_waitcnt lgkmcnt(0)
	v_mfma_f32_16x16x32_bf16 v[94:97], v[130:133], v[186:189], 0
	v_mfma_f32_16x16x32_bf16 v[30:33], v[138:141], v[186:189], 0
	v_mfma_f32_16x16x32_bf16 v[90:93], v[130:133], v[194:197], 0
	v_mfma_f32_16x16x32_bf16 v[26:29], v[138:141], v[194:197], 0
	v_mfma_f32_16x16x32_bf16 v[78:81], v[130:133], v[202:205], 0
	v_mfma_f32_16x16x32_bf16 v[14:17], v[138:141], v[202:205], 0
	v_mfma_f32_16x16x32_bf16 v[74:77], v[130:133], v[210:213], 0
	v_mfma_f32_16x16x32_bf16 v[10:13], v[138:141], v[210:213], 0
	v_mfma_f32_16x16x32_bf16 v[94:97], v[134:137], v[190:193], v[94:97]
	v_mfma_f32_16x16x32_bf16 v[30:33], v[142:145], v[190:193], v[30:33]
	v_mfma_f32_16x16x32_bf16 v[90:93], v[134:137], v[198:201], v[90:93]
	v_mfma_f32_16x16x32_bf16 v[26:29], v[142:145], v[198:201], v[26:29]
	v_mfma_f32_16x16x32_bf16 v[78:81], v[134:137], v[206:209], v[78:81]
	v_mfma_f32_16x16x32_bf16 v[14:17], v[142:145], v[206:209], v[14:17]
	v_mfma_f32_16x16x32_bf16 v[74:77], v[134:137], v[214:217], v[74:77]
	v_mfma_f32_16x16x32_bf16 v[10:13], v[142:145], v[214:217], v[10:13]
	v_mfma_f32_16x16x32_bf16 v[86:89], v[158:161], v[186:189], 0
	v_mfma_f32_16x16x32_bf16 v[22:25], v[178:181], v[186:189], 0
	v_mfma_f32_16x16x32_bf16 v[82:85], v[158:161], v[194:197], 0
	v_mfma_f32_16x16x32_bf16 v[18:21], v[178:181], v[194:197], 0
	v_mfma_f32_16x16x32_bf16 v[70:73], v[158:161], v[202:205], 0
	v_mfma_f32_16x16x32_bf16 v[6:9], v[178:181], v[202:205], 0
	v_mfma_f32_16x16x32_bf16 v[66:69], v[158:161], v[210:213], 0
	v_mfma_f32_16x16x32_bf16 v[2:5], v[178:181], v[210:213], 0
	v_mfma_f32_16x16x32_bf16 v[86:89], v[174:177], v[190:193], v[86:89]
	v_mfma_f32_16x16x32_bf16 v[22:25], v[182:185], v[190:193], v[22:25]
	v_mfma_f32_16x16x32_bf16 v[82:85], v[174:177], v[198:201], v[82:85]
	v_mfma_f32_16x16x32_bf16 v[18:21], v[182:185], v[198:201], v[18:21]
	v_mfma_f32_16x16x32_bf16 v[70:73], v[174:177], v[206:209], v[70:73]
	v_mfma_f32_16x16x32_bf16 v[6:9], v[182:185], v[206:209], v[6:9]
	v_mfma_f32_16x16x32_bf16 v[66:69], v[174:177], v[214:217], v[66:69]
	v_mfma_f32_16x16x32_bf16 v[2:5], v[182:185], v[214:217], v[2:5]
	s_barrier
	s_add_i32 s61, 0, 0x18000
	s_add_i32 s64, 0, 0x1c000
	v_add_u32_e32 v142, s61, v248
	v_add_u32_e32 v182, s64, v248
	ds_read_b128 v[130:133], v142
	ds_read_b128 v[134:137], v142 offset:1024
	ds_read_b128 v[138:141], v142 offset:2048
	ds_read_b128 v[142:145], v142 offset:3072
	ds_read_b128 v[158:161], v182
	ds_read_b128 v[174:177], v182 offset:1024
	ds_read_b128 v[178:181], v182 offset:2048
	ds_read_b128 v[182:185], v182 offset:3072
	s_add_u32 s94, vcc_lo, 0x80000
	s_addc_u32 s95, vcc_hi, 0
	s_mov_b32 m0, s87
	v_lshl_add_u64 v[226:227], s[94:95], 0, v[146:147]
	ds_read_b128 v[186:189], v251 offset:32768
	ds_read_b128 v[190:193], v251 offset:33792
	ds_read_b128 v[194:197], v251 offset:34816
	ds_read_b128 v[198:201], v251 offset:35840
	ds_read_b128 v[202:205], v251 offset:36864
	ds_read_b128 v[206:209], v251 offset:37888
	ds_read_b128 v[210:213], v251 offset:38912
	ds_read_b128 v[214:217], v251 offset:39936
	global_load_lds_dwordx4 v[226:227], off
	v_lshl_add_u64 v[226:227], s[94:95], 0, v[148:149]
	s_mov_b32 m0, s88
	s_nop 0
	global_load_lds_dwordx4 v[226:227], off
	s_waitcnt vmcnt(8)
	s_waitcnt lgkmcnt(0)
	s_barrier
	s_waitcnt lgkmcnt(0)
	v_mfma_f32_16x16x32_bf16 v[126:129], v[130:133], v[186:189], v[126:129]
	v_mfma_f32_16x16x32_bf16 v[62:65], v[138:141], v[186:189], v[62:65]
	v_mfma_f32_16x16x32_bf16 v[118:121], v[130:133], v[194:197], v[118:121]
	v_mfma_f32_16x16x32_bf16 v[58:61], v[138:141], v[194:197], v[58:61]
	v_mfma_f32_16x16x32_bf16 v[110:113], v[130:133], v[202:205], v[110:113]
	v_mfma_f32_16x16x32_bf16 v[46:49], v[138:141], v[202:205], v[46:49]
	v_mfma_f32_16x16x32_bf16 v[106:109], v[130:133], v[210:213], v[106:109]
	v_mfma_f32_16x16x32_bf16 v[42:45], v[138:141], v[210:213], v[42:45]
	v_mfma_f32_16x16x32_bf16 v[126:129], v[134:137], v[190:193], v[126:129]
	v_mfma_f32_16x16x32_bf16 v[62:65], v[142:145], v[190:193], v[62:65]
	v_mfma_f32_16x16x32_bf16 v[118:121], v[134:137], v[198:201], v[118:121]
	v_mfma_f32_16x16x32_bf16 v[58:61], v[142:145], v[198:201], v[58:61]
	v_mfma_f32_16x16x32_bf16 v[110:113], v[134:137], v[206:209], v[110:113]
	v_mfma_f32_16x16x32_bf16 v[46:49], v[142:145], v[206:209], v[46:49]
	v_mfma_f32_16x16x32_bf16 v[106:109], v[134:137], v[214:217], v[106:109]
	v_mfma_f32_16x16x32_bf16 v[42:45], v[142:145], v[214:217], v[42:45]
	v_mfma_f32_16x16x32_bf16 v[122:125], v[158:161], v[186:189], v[122:125]
	v_mfma_f32_16x16x32_bf16 v[54:57], v[178:181], v[186:189], v[54:57]
	v_mfma_f32_16x16x32_bf16 v[114:117], v[158:161], v[194:197], v[114:117]
	v_mfma_f32_16x16x32_bf16 v[50:53], v[178:181], v[194:197], v[50:53]
	v_mfma_f32_16x16x32_bf16 v[102:105], v[158:161], v[202:205], v[102:105]
	v_mfma_f32_16x16x32_bf16 v[38:41], v[178:181], v[202:205], v[38:41]
	v_mfma_f32_16x16x32_bf16 v[98:101], v[158:161], v[210:213], v[98:101]
	v_mfma_f32_16x16x32_bf16 v[34:37], v[178:181], v[210:213], v[34:37]
	v_mfma_f32_16x16x32_bf16 v[122:125], v[174:177], v[190:193], v[122:125]
	v_mfma_f32_16x16x32_bf16 v[54:57], v[182:185], v[190:193], v[54:57]
	v_mfma_f32_16x16x32_bf16 v[114:117], v[174:177], v[198:201], v[114:117]
	v_mfma_f32_16x16x32_bf16 v[50:53], v[182:185], v[198:201], v[50:53]
	v_mfma_f32_16x16x32_bf16 v[102:105], v[174:177], v[206:209], v[102:105]
	v_mfma_f32_16x16x32_bf16 v[38:41], v[182:185], v[206:209], v[38:41]
	v_mfma_f32_16x16x32_bf16 v[98:101], v[174:177], v[214:217], v[98:101]
	v_mfma_f32_16x16x32_bf16 v[34:37], v[182:185], v[214:217], v[34:37]
	s_barrier
; #define PG8_STAGE(bufoff, gbase, voff) do { _Pragma("unroll") for (int _i = 0; _i < 2; ++_i) \
;         __builtin_amdgcn_global_load_lds((const __attribute__((address_space(1))) unsigned*)((const char*)(gbase) + (voff)[_i]), (LAS unsigned*)(lds + (bufoff) + ldsw + _i * 8192), 16, 0, 0); } while (0)
; #define PG8_LDA(dst, b, h) do { _Pragma("unroll") for (int m = 0; m < 4; ++m) _Pragma("unroll") for (int k = 0; k < 2; ++k) dst[m][k] = *(const LAS bf16x8*)(lds + PG8_SA(b, h) + aoff + m * 2048 + k * 1024); } while (0)
; #define PG8_MMA(ai, bj, At, Bt) do { __builtin_amdgcn_s_setprio(1); _Pragma("unroll") for (int m = 0; m < 4; ++m) _Pragma("unroll") for (int n = 0; n < 2; ++n) _Pragma("unroll") for (int k = 0; k < 2; ++k) \
;         acc[ai][bj][m][n] = __builtin_amdgcn_mfma_f32_16x16x32_bf16(Bt[n][k], At[m][k], acc[ai][bj][m][n], 0, 0, 0); __builtin_amdgcn_s_setprio(0); } while (0)
; #define PG8_WAIT_V(n) asm volatile("s_waitcnt vmcnt(" #n ")" ::: "memory")
; #define PG8_WAIT_L(n) asm volatile("s_waitcnt lgkmcnt(" #n ")" ::: "memory")
; #define PG8_BAR __builtin_amdgcn_s_barrier()
; #define PG8_SCHED __builtin_amdgcn_sched_barrier(0)
; template <class Epi, class SchedT, bool ALIGN_EPI, bool SP2>
; __device__ __forceinline__ void gemm_phase(LAS unsigned char* lds, const int ldk, const int nt, const SchedT& S, const Epi& E) {
;     ...
;             PG8_LDA(At, 1, 1); PG8_STAGE(PG8_SB(1, 0), b3, voffB); PG8_STAGE(PG8_SB(1, 1), b3 + hstepB, voffB); PG8_STAGE(PG8_SA(1, 0), a3, voffA);
;             PG8_WAIT_V(8); PG8_WAIT_L(0); PG8_BAR; PG8_MMA(1, 0, At, B0); PG8_MMA(1, 1, At, B1); PG8_BAR; PG8_SCHED;
	s_add_i32 s61, s61, s84
	v_lshl_add_u64 v[218:219], v[218:219], 0, s[24:25]
	s_mov_b32 m0, s61
	ds_read_b128 v[186:189], v251 offset:49152
	ds_read_b128 v[190:193], v251 offset:50176
	ds_read_b128 v[194:197], v251 offset:51200
	ds_read_b128 v[198:201], v251 offset:52224
	ds_read_b128 v[202:205], v251 offset:53248
	ds_read_b128 v[206:209], v251 offset:54272
	ds_read_b128 v[210:213], v251 offset:55296
	ds_read_b128 v[214:217], v251 offset:56320
	global_load_lds_dwordx4 v[218:219], off
	s_add_i32 m0, s61, 0x2000
	s_add_u32 s36, s36, 0x20080
	v_lshl_add_u64 v[218:219], v[220:221], 0, s[24:25]
	s_addc_u32 s37, s37, 0
	s_add_i32 s61, s64, s84
	global_load_lds_dwordx4 v[218:219], off
	v_lshl_add_u64 v[218:219], s[36:37], 0, v[0:1]
	s_mov_b32 m0, s61
	s_nop 0
	global_load_lds_dwordx4 v[218:219], off
	v_lshl_add_u64 v[218:219], s[36:37], 0, v[150:151]
	s_add_i32 m0, s61, 0x2000
	s_nop 0
	global_load_lds_dwordx4 v[218:219], off
	v_lshl_add_u64 v[218:219], v[222:223], 0, s[24:25]
	s_mov_b32 m0, s89
	s_nop 0
	global_load_lds_dwordx4 v[218:219], off
	v_lshl_add_u64 v[218:219], v[224:225], 0, s[24:25]
	s_mov_b32 m0, s90
	s_nop 0
	global_load_lds_dwordx4 v[218:219], off
	s_waitcnt vmcnt(8)
	s_waitcnt lgkmcnt(0)
	s_barrier
	s_waitcnt lgkmcnt(0)
	v_mfma_f32_16x16x32_bf16 v[94:97], v[130:133], v[186:189], v[94:97]
	v_mfma_f32_16x16x32_bf16 v[30:33], v[138:141], v[186:189], v[30:33]
	v_mfma_f32_16x16x32_bf16 v[90:93], v[130:133], v[194:197], v[90:93]
	v_mfma_f32_16x16x32_bf16 v[26:29], v[138:141], v[194:197], v[26:29]
	v_mfma_f32_16x16x32_bf16 v[78:81], v[130:133], v[202:205], v[78:81]
	v_mfma_f32_16x16x32_bf16 v[14:17], v[138:141], v[202:205], v[14:17]
	v_mfma_f32_16x16x32_bf16 v[74:77], v[130:133], v[210:213], v[74:77]
	v_mfma_f32_16x16x32_bf16 v[10:13], v[138:141], v[210:213], v[10:13]
	v_mfma_f32_16x16x32_bf16 v[94:97], v[134:137], v[190:193], v[94:97]
	v_mfma_f32_16x16x32_bf16 v[30:33], v[142:145], v[190:193], v[30:33]
	v_mfma_f32_16x16x32_bf16 v[90:93], v[134:137], v[198:201], v[90:93]
	v_mfma_f32_16x16x32_bf16 v[26:29], v[142:145], v[198:201], v[26:29]
	v_mfma_f32_16x16x32_bf16 v[78:81], v[134:137], v[206:209], v[78:81]
	v_mfma_f32_16x16x32_bf16 v[14:17], v[142:145], v[206:209], v[14:17]
	v_mfma_f32_16x16x32_bf16 v[74:77], v[134:137], v[214:217], v[74:77]
	v_mfma_f32_16x16x32_bf16 v[10:13], v[142:145], v[214:217], v[10:13]
	v_mfma_f32_16x16x32_bf16 v[86:89], v[158:161], v[186:189], v[86:89]
	v_mfma_f32_16x16x32_bf16 v[22:25], v[178:181], v[186:189], v[22:25]
	v_mfma_f32_16x16x32_bf16 v[82:85], v[158:161], v[194:197], v[82:85]
	v_mfma_f32_16x16x32_bf16 v[18:21], v[178:181], v[194:197], v[18:21]
	v_mfma_f32_16x16x32_bf16 v[70:73], v[158:161], v[202:205], v[70:73]
	v_mfma_f32_16x16x32_bf16 v[6:9], v[178:181], v[202:205], v[6:9]
	v_mfma_f32_16x16x32_bf16 v[66:69], v[158:161], v[210:213], v[66:69]
	v_mfma_f32_16x16x32_bf16 v[2:5], v[178:181], v[210:213], v[2:5]
	v_mfma_f32_16x16x32_bf16 v[86:89], v[174:177], v[190:193], v[86:89]
	v_mfma_f32_16x16x32_bf16 v[22:25], v[182:185], v[190:193], v[22:25]
	v_mfma_f32_16x16x32_bf16 v[82:85], v[174:177], v[198:201], v[82:85]
	v_mfma_f32_16x16x32_bf16 v[18:21], v[182:185], v[198:201], v[18:21]
	v_mfma_f32_16x16x32_bf16 v[70:73], v[174:177], v[206:209], v[70:73]
	v_mfma_f32_16x16x32_bf16 v[6:9], v[182:185], v[206:209], v[6:9]
	v_mfma_f32_16x16x32_bf16 v[66:69], v[174:177], v[214:217], v[66:69]
	v_mfma_f32_16x16x32_bf16 v[2:5], v[182:185], v[214:217], v[2:5]
	s_barrier
	s_add_i32 s59, s59, 2
	s_add_u32 s34, s34, 0x100
	s_addc_u32 s35, s35, 0
	s_add_u32 s13, s13, 0x100
	s_addc_u32 s17, s17, 0
	s_cmp_gt_u32 s59, 29

; #define PG8_STAGE(bufoff, gbase, voff) do { _Pragma("unroll") for (int _i = 0; _i < 2; ++_i) \
;         __builtin_amdgcn_global_load_lds((const __attribute__((address_space(1))) unsigned*)((const char*)(gbase) + (voff)[_i]), (LAS unsigned*)(lds + (bufoff) + ldsw + _i * 8192), 16, 0, 0); } while (0)
; #define PG8_LDA(dst, b, h) do { _Pragma("unroll") for (int m = 0; m < 4; ++m) _Pragma("unroll") for (int k = 0; k < 2; ++k) dst[m][k] = *(const LAS bf16x8*)(lds + PG8_SA(b, h) + aoff + m * 2048 + k * 1024); } while (0)
; #define PG8_LDB(dst, b, h) do { _Pragma("unroll") for (int n = 0; n < 2; ++n) _Pragma("unroll") for (int k = 0; k < 2; ++k) dst[n][k] = *(const LAS bf16x8*)(lds + PG8_SB(b, h) + boff + n * 2048 + k * 1024); } while (0)
; #define PG8_MMA(ai, bj, At, Bt) do { __builtin_amdgcn_s_setprio(1); _Pragma("unroll") for (int m = 0; m < 4; ++m) _Pragma("unroll") for (int n = 0; n < 2; ++n) _Pragma("unroll") for (int k = 0; k < 2; ++k) \
;         acc[ai][bj][m][n] = __builtin_amdgcn_mfma_f32_16x16x32_bf16(Bt[n][k], At[m][k], acc[ai][bj][m][n], 0, 0, 0); __builtin_amdgcn_s_setprio(0); } while (0)
; #define PG8_WAIT_V(n) asm volatile("s_waitcnt vmcnt(" #n ")" ::: "memory")
; #define PG8_WAIT_L(n) asm volatile("s_waitcnt lgkmcnt(" #n ")" ::: "memory")
; #define PG8_BAR __builtin_amdgcn_s_barrier()
; template <class Epi, class SchedT, bool ALIGN_EPI, bool SP2>
; __device__ __forceinline__ void gemm_phase(LAS unsigned char* lds, const int ldk, const int nt, const SchedT& S, const Epi& E) {
;     ...
;             const bool last = (t == nt - 2);
;             const char* a1 = cA + (size_t)(t + 1) * kstep;
;             const char* a2 = last ? nA : cA + (size_t)(t + 2) * kstep; const char* b2 = last ? nB : cB + (size_t)(t + 2) * kstep;
;             const char* a3 = a2 + kstep; const char* b3 = b2 + kstep;
;             if constexpr (SP2) {
;             PG8_LDB(B0, 0, 0); PG8_LDB(B1, 0, 1); PG8_SCHED; PG8_LDA(At, 0, 0); PG8_STAGE(PG8_SA(1, 1), a1 + hstep, voffA);
;             PG8_WAIT_V(8); PG8_WAIT_L(0); PG8_BAR; PG8_MMA(0, 0, At, B0); PG8_MMA(0, 1, At, B1); PG8_BAR; PG8_SCHED;
;             PG8_LDA(At, 0, 1); PG8_STAGE(PG8_SB(0, 0), b2, voffB); PG8_STAGE(PG8_SB(0, 1), b2 + hstepB, voffB); PG8_STAGE(PG8_SA(0, 0), a2, voffA);
;             PG8_WAIT_V(8); PG8_WAIT_L(0); PG8_BAR; PG8_MMA(1, 0, At, B0); PG8_MMA(1, 1, At, B1); PG8_BAR; PG8_SCHED;
.LBB0_947:
	s_add_u32 s81, s16, 0x100
	s_addc_u32 s82, s17, 0
	s_mov_b32 s83, -2
	s_waitcnt lgkmcnt(0)
	s_add_u32 s16, s12, 0x100
	s_addc_u32 s17, s13, 0
	s_add_i32 s64, 0, 0x10000
	s_cmpk_eq_i32 s83, 0x52
	s_cselect_b32 s47, s1, s17
	s_cselect_b32 s46, s0, s16
	v_add_u32_e32 v144, s64, v147
	s_cselect_b32 s45, s43, s82
	s_cselect_b32 s44, s42, s81
	s_add_i32 s65, 0, 0x14000
	ds_read_b128 v[140:143], v144
	ds_read_b128 v[150:153], v144 offset:1024
	ds_read_b128 v[154:157], v144 offset:2048
	ds_read_b128 v[158:161], v144 offset:3072
	v_add_u32_e32 v144, s65, v147
	ds_read_b128 v[174:177], v144
	ds_read_b128 v[178:181], v144 offset:1024
	ds_read_b128 v[182:185], v144 offset:2048
	ds_read_b128 v[186:189], v144 offset:3072
	v_lshl_add_u64 v[144:145], s[12:13], 0, v[136:137]
	s_add_i32 m0, s53, 0xc000
	ds_read_b128 v[190:193], v149
	ds_read_b128 v[194:197], v149 offset:1024
	ds_read_b128 v[198:201], v149 offset:2048
	ds_read_b128 v[202:205], v149 offset:3072
	ds_read_b128 v[206:209], v149 offset:4096
	ds_read_b128 v[210:213], v149 offset:5120
	ds_read_b128 v[214:217], v149 offset:6144
	ds_read_b128 v[218:221], v149 offset:7168
	global_load_lds_dwordx4 v[144:145], off
	v_lshl_add_u64 v[144:145], s[12:13], 0, v[138:139]
	s_add_i32 m0, s53, 0xe000
	s_nop 0
	global_load_lds_dwordx4 v[144:145], off
	s_waitcnt vmcnt(8)
	s_waitcnt lgkmcnt(0)
	s_barrier
	s_waitcnt lgkmcnt(0)
	v_mfma_f32_16x16x32_bf16 v[126:129], v[140:143], v[190:193], 0
	v_mfma_f32_16x16x32_bf16 v[122:125], v[154:157], v[190:193], 0
	v_mfma_f32_16x16x32_bf16 v[110:113], v[140:143], v[198:201], 0
	v_mfma_f32_16x16x32_bf16 v[106:109], v[154:157], v[198:201], 0
	v_mfma_f32_16x16x32_bf16 v[94:97], v[140:143], v[206:209], 0
	v_mfma_f32_16x16x32_bf16 v[90:93], v[154:157], v[206:209], 0
	v_mfma_f32_16x16x32_bf16 v[78:81], v[140:143], v[214:217], 0
	v_mfma_f32_16x16x32_bf16 v[74:77], v[154:157], v[214:217], 0
	v_mfma_f32_16x16x32_bf16 v[126:129], v[150:153], v[194:197], v[126:129]
	v_mfma_f32_16x16x32_bf16 v[122:125], v[158:161], v[194:197], v[122:125]
	v_mfma_f32_16x16x32_bf16 v[110:113], v[150:153], v[202:205], v[110:113]
	v_mfma_f32_16x16x32_bf16 v[106:109], v[158:161], v[202:205], v[106:109]
	v_mfma_f32_16x16x32_bf16 v[94:97], v[150:153], v[210:213], v[94:97]
	v_mfma_f32_16x16x32_bf16 v[90:93], v[158:161], v[210:213], v[90:93]
	v_mfma_f32_16x16x32_bf16 v[78:81], v[150:153], v[218:221], v[78:81]
	v_mfma_f32_16x16x32_bf16 v[74:77], v[158:161], v[218:221], v[74:77]
	v_mfma_f32_16x16x32_bf16 v[118:121], v[174:177], v[190:193], 0
	v_mfma_f32_16x16x32_bf16 v[114:117], v[182:185], v[190:193], 0
	v_mfma_f32_16x16x32_bf16 v[102:105], v[174:177], v[198:201], 0
	v_mfma_f32_16x16x32_bf16 v[98:101], v[182:185], v[198:201], 0
	v_mfma_f32_16x16x32_bf16 v[86:89], v[174:177], v[206:209], 0
	v_mfma_f32_16x16x32_bf16 v[82:85], v[182:185], v[206:209], 0
	v_mfma_f32_16x16x32_bf16 v[70:73], v[174:177], v[214:217], 0
	v_mfma_f32_16x16x32_bf16 v[66:69], v[182:185], v[214:217], 0
	v_mfma_f32_16x16x32_bf16 v[118:121], v[178:181], v[194:197], v[118:121]
	v_mfma_f32_16x16x32_bf16 v[114:117], v[186:189], v[194:197], v[114:117]
	v_mfma_f32_16x16x32_bf16 v[102:105], v[178:181], v[202:205], v[102:105]
	v_mfma_f32_16x16x32_bf16 v[98:101], v[186:189], v[202:205], v[98:101]
	v_mfma_f32_16x16x32_bf16 v[86:89], v[178:181], v[210:213], v[86:89]
	v_mfma_f32_16x16x32_bf16 v[82:85], v[186:189], v[210:213], v[82:85]
	v_mfma_f32_16x16x32_bf16 v[70:73], v[178:181], v[218:221], v[70:73]
	v_mfma_f32_16x16x32_bf16 v[66:69], v[186:189], v[218:221], v[66:69]
	s_barrier
	s_add_i32 s12, s64, s52
	v_lshl_add_u64 v[144:145], s[44:45], 0, v[0:1]
	s_mov_b32 m0, s12
	ds_read_b128 v[190:193], v149 offset:16384
	ds_read_b128 v[194:197], v149 offset:17408
	ds_read_b128 v[198:201], v149 offset:18432
	ds_read_b128 v[202:205], v149 offset:19456
	ds_read_b128 v[206:209], v149 offset:20480
	ds_read_b128 v[210:213], v149 offset:21504
	ds_read_b128 v[214:217], v149 offset:22528
	ds_read_b128 v[218:221], v149 offset:23552
	global_load_lds_dwordx4 v[144:145], off
	s_add_i32 m0, s12, 0x2000
	s_add_u32 s12, s44, 0x56000
	v_lshl_add_u64 v[222:223], s[44:45], 0, v[134:135]
	s_addc_u32 s13, s45, 0
	s_add_i32 s64, s65, s52
	global_load_lds_dwordx4 v[222:223], off
	v_lshl_add_u64 v[224:225], s[12:13], 0, v[0:1]
	s_mov_b32 m0, s64
	v_lshl_add_u64 v[226:227], s[46:47], 0, v[132:133]
	global_load_lds_dwordx4 v[224:225], off
	v_lshl_add_u64 v[224:225], s[12:13], 0, v[134:135]
	s_add_i32 m0, s64, 0x2000
	s_nop 0
	global_load_lds_dwordx4 v[224:225], off
	v_lshl_add_u64 v[224:225], s[46:47], 0, v[130:131]
	s_mov_b32 m0, s53
	s_nop 0
	global_load_lds_dwordx4 v[224:225], off
	s_mov_b32 m0, s54
	s_nop 0
	global_load_lds_dwordx4 v[226:227], off
	s_waitcnt vmcnt(8)
	s_waitcnt lgkmcnt(0)
	s_barrier
; #define PG8_STAGE(bufoff, gbase, voff) do { _Pragma("unroll") for (int _i = 0; _i < 2; ++_i) \
;         __builtin_amdgcn_global_load_lds((const __attribute__((address_space(1))) unsigned*)((const char*)(gbase) + (voff)[_i]), (LAS unsigned*)(lds + (bufoff) + ldsw + _i * 8192), 16, 0, 0); } while (0)
; #define PG8_LDA(dst, b, h) do { _Pragma("unroll") for (int m = 0; m < 4; ++m) _Pragma("unroll") for (int k = 0; k < 2; ++k) dst[m][k] = *(const LAS bf16x8*)(lds + PG8_SA(b, h) + aoff + m * 2048 + k * 1024); } while (0)
; #define PG8_LDB(dst, b, h) do { _Pragma("unroll") for (int n = 0; n < 2; ++n) _Pragma("unroll") for (int k = 0; k < 2; ++k) dst[n][k] = *(const LAS bf16x8*)(lds + PG8_SB(b, h) + boff + n * 2048 + k * 1024); } while (0)
; #define PG8_MMA(ai, bj, At, Bt) do { __builtin_amdgcn_s_setprio(1); _Pragma("unroll") for (int m = 0; m < 4; ++m) _Pragma("unroll") for (int n = 0; n < 2; ++n) _Pragma("unroll") for (int k = 0; k < 2; ++k) \
;         acc[ai][bj][m][n] = __builtin_amdgcn_mfma_f32_16x16x32_bf16(Bt[n][k], At[m][k], acc[ai][bj][m][n], 0, 0, 0); __builtin_amdgcn_s_setprio(0); } while (0)
; #define PG8_WAIT_V(n) asm volatile("s_waitcnt vmcnt(" #n ")" ::: "memory")
; #define PG8_WAIT_L(n) asm volatile("s_waitcnt lgkmcnt(" #n ")" ::: "memory")
; #define PG8_BAR __builtin_amdgcn_s_barrier()
; #define PG8_SCHED __builtin_amdgcn_sched_barrier(0)
; template <class Epi, class SchedT, bool ALIGN_EPI, bool SP2>
; __device__ __forceinline__ void gemm_phase(LAS unsigned char* lds, const int ldk, const int nt, const SchedT& S, const Epi& E) {
;     ...
;             PG8_WAIT_V(8); PG8_WAIT_L(0); PG8_BAR; PG8_MMA(1, 0, At, B0); PG8_MMA(1, 1, At, B1); PG8_BAR; PG8_SCHED;
;             PG8_LDB(B0, 1, 0); PG8_LDB(B1, 1, 1); PG8_SCHED; PG8_LDA(At, 1, 0); PG8_STAGE(PG8_SA(0, 1), a2 + hstep, voffA);
;             PG8_WAIT_V(8); PG8_WAIT_L(0); PG8_BAR; PG8_MMA(0, 0, At, B0); PG8_MMA(0, 1, At, B1); PG8_BAR; PG8_SCHED;
	s_waitcnt lgkmcnt(0)
	v_mfma_f32_16x16x32_bf16 v[62:65], v[140:143], v[190:193], 0
	v_mfma_f32_16x16x32_bf16 v[58:61], v[154:157], v[190:193], 0
	v_mfma_f32_16x16x32_bf16 v[46:49], v[140:143], v[198:201], 0
	v_mfma_f32_16x16x32_bf16 v[42:45], v[154:157], v[198:201], 0
	v_mfma_f32_16x16x32_bf16 v[30:33], v[140:143], v[206:209], 0
	v_mfma_f32_16x16x32_bf16 v[26:29], v[154:157], v[206:209], 0
	v_mfma_f32_16x16x32_bf16 v[14:17], v[140:143], v[214:217], 0
	v_mfma_f32_16x16x32_bf16 v[10:13], v[154:157], v[214:217], 0
	v_mfma_f32_16x16x32_bf16 v[62:65], v[150:153], v[194:197], v[62:65]
	v_mfma_f32_16x16x32_bf16 v[58:61], v[158:161], v[194:197], v[58:61]
	v_mfma_f32_16x16x32_bf16 v[46:49], v[150:153], v[202:205], v[46:49]
	v_mfma_f32_16x16x32_bf16 v[42:45], v[158:161], v[202:205], v[42:45]
	v_mfma_f32_16x16x32_bf16 v[30:33], v[150:153], v[210:213], v[30:33]
	v_mfma_f32_16x16x32_bf16 v[26:29], v[158:161], v[210:213], v[26:29]
	v_mfma_f32_16x16x32_bf16 v[14:17], v[150:153], v[218:221], v[14:17]
	v_mfma_f32_16x16x32_bf16 v[10:13], v[158:161], v[218:221], v[10:13]
	v_mfma_f32_16x16x32_bf16 v[54:57], v[174:177], v[190:193], 0
	v_mfma_f32_16x16x32_bf16 v[50:53], v[182:185], v[190:193], 0
	v_mfma_f32_16x16x32_bf16 v[38:41], v[174:177], v[198:201], 0
	v_mfma_f32_16x16x32_bf16 v[34:37], v[182:185], v[198:201], 0
	v_mfma_f32_16x16x32_bf16 v[22:25], v[174:177], v[206:209], 0
	v_mfma_f32_16x16x32_bf16 v[18:21], v[182:185], v[206:209], 0
	v_mfma_f32_16x16x32_bf16 v[6:9], v[174:177], v[214:217], 0
	v_mfma_f32_16x16x32_bf16 v[2:5], v[182:185], v[214:217], 0
	v_mfma_f32_16x16x32_bf16 v[54:57], v[178:181], v[194:197], v[54:57]
	v_mfma_f32_16x16x32_bf16 v[50:53], v[186:189], v[194:197], v[50:53]
	v_mfma_f32_16x16x32_bf16 v[38:41], v[178:181], v[202:205], v[38:41]
	v_mfma_f32_16x16x32_bf16 v[34:37], v[186:189], v[202:205], v[34:37]
	v_mfma_f32_16x16x32_bf16 v[22:25], v[178:181], v[210:213], v[22:25]
	v_mfma_f32_16x16x32_bf16 v[18:21], v[186:189], v[210:213], v[18:21]
	v_mfma_f32_16x16x32_bf16 v[6:9], v[178:181], v[218:221], v[6:9]
	v_mfma_f32_16x16x32_bf16 v[2:5], v[186:189], v[218:221], v[2:5]
	s_barrier
	s_add_i32 s64, 0, 0x18000
	s_add_i32 s65, 0, 0x1c000
	v_add_u32_e32 v158, s64, v147
	v_add_u32_e32 v186, s65, v147
	ds_read_b128 v[140:143], v158
	ds_read_b128 v[150:153], v158 offset:1024
	ds_read_b128 v[154:157], v158 offset:2048
	ds_read_b128 v[158:161], v158 offset:3072
	ds_read_b128 v[174:177], v186
	ds_read_b128 v[178:181], v186 offset:1024
	ds_read_b128 v[182:185], v186 offset:2048
	ds_read_b128 v[186:189], v186 offset:3072
	s_add_u32 s12, s46, 0x158000
	s_addc_u32 s13, s47, 0
	s_mov_b32 m0, s55
	v_lshl_add_u64 v[228:229], s[12:13], 0, v[130:131]
	ds_read_b128 v[190:193], v149 offset:32768
	ds_read_b128 v[194:197], v149 offset:33792
	ds_read_b128 v[198:201], v149 offset:34816
	ds_read_b128 v[202:205], v149 offset:35840
	ds_read_b128 v[206:209], v149 offset:36864
	ds_read_b128 v[210:213], v149 offset:37888
	ds_read_b128 v[214:217], v149 offset:38912
	ds_read_b128 v[218:221], v149 offset:39936
	global_load_lds_dwordx4 v[228:229], off
	v_lshl_add_u64 v[228:229], s[12:13], 0, v[132:133]
	s_mov_b32 m0, s56
	s_nop 0
	global_load_lds_dwordx4 v[228:229], off
	s_waitcnt vmcnt(8)
	s_waitcnt lgkmcnt(0)
	s_barrier
	s_waitcnt lgkmcnt(0)
	v_mfma_f32_16x16x32_bf16 v[126:129], v[140:143], v[190:193], v[126:129]
	v_mfma_f32_16x16x32_bf16 v[122:125], v[154:157], v[190:193], v[122:125]
	v_mfma_f32_16x16x32_bf16 v[110:113], v[140:143], v[198:201], v[110:113]
	v_mfma_f32_16x16x32_bf16 v[106:109], v[154:157], v[198:201], v[106:109]
	v_mfma_f32_16x16x32_bf16 v[94:97], v[140:143], v[206:209], v[94:97]
	v_mfma_f32_16x16x32_bf16 v[90:93], v[154:157], v[206:209], v[90:93]
	v_mfma_f32_16x16x32_bf16 v[78:81], v[140:143], v[214:217], v[78:81]
	v_mfma_f32_16x16x32_bf16 v[74:77], v[154:157], v[214:217], v[74:77]
	v_mfma_f32_16x16x32_bf16 v[126:129], v[150:153], v[194:197], v[126:129]
	v_mfma_f32_16x16x32_bf16 v[122:125], v[158:161], v[194:197], v[122:125]
	v_mfma_f32_16x16x32_bf16 v[110:113], v[150:153], v[202:205], v[110:113]
	v_mfma_f32_16x16x32_bf16 v[106:109], v[158:161], v[202:205], v[106:109]
	v_mfma_f32_16x16x32_bf16 v[94:97], v[150:153], v[210:213], v[94:97]
	v_mfma_f32_16x16x32_bf16 v[90:93], v[158:161], v[210:213], v[90:93]
	v_mfma_f32_16x16x32_bf16 v[78:81], v[150:153], v[218:221], v[78:81]
	v_mfma_f32_16x16x32_bf16 v[74:77], v[158:161], v[218:221], v[74:77]
	v_mfma_f32_16x16x32_bf16 v[118:121], v[174:177], v[190:193], v[118:121]
	v_mfma_f32_16x16x32_bf16 v[114:117], v[182:185], v[190:193], v[114:117]
	v_mfma_f32_16x16x32_bf16 v[102:105], v[174:177], v[198:201], v[102:105]
	v_mfma_f32_16x16x32_bf16 v[98:101], v[182:185], v[198:201], v[98:101]
	v_mfma_f32_16x16x32_bf16 v[86:89], v[174:177], v[206:209], v[86:89]
	v_mfma_f32_16x16x32_bf16 v[82:85], v[182:185], v[206:209], v[82:85]
	v_mfma_f32_16x16x32_bf16 v[70:73], v[174:177], v[214:217], v[70:73]
	v_mfma_f32_16x16x32_bf16 v[66:69], v[182:185], v[214:217], v[66:69]
	v_mfma_f32_16x16x32_bf16 v[118:121], v[178:181], v[194:197], v[118:121]
	v_mfma_f32_16x16x32_bf16 v[114:117], v[186:189], v[194:197], v[114:117]
	v_mfma_f32_16x16x32_bf16 v[102:105], v[178:181], v[202:205], v[102:105]
	v_mfma_f32_16x16x32_bf16 v[98:101], v[186:189], v[202:205], v[98:101]
	v_mfma_f32_16x16x32_bf16 v[86:89], v[178:181], v[210:213], v[86:89]
	v_mfma_f32_16x16x32_bf16 v[82:85], v[186:189], v[210:213], v[82:85]
	v_mfma_f32_16x16x32_bf16 v[70:73], v[178:181], v[218:221], v[70:73]
	v_mfma_f32_16x16x32_bf16 v[66:69], v[186:189], v[218:221], v[66:69]
	s_barrier
; #define PG8_STAGE(bufoff, gbase, voff) do { _Pragma("unroll") for (int _i = 0; _i < 2; ++_i) \
;         __builtin_amdgcn_global_load_lds((const __attribute__((address_space(1))) unsigned*)((const char*)(gbase) + (voff)[_i]), (LAS unsigned*)(lds + (bufoff) + ldsw + _i * 8192), 16, 0, 0); } while (0)
; #define PG8_LDA(dst, b, h) do { _Pragma("unroll") for (int m = 0; m < 4; ++m) _Pragma("unroll") for (int k = 0; k < 2; ++k) dst[m][k] = *(const LAS bf16x8*)(lds + PG8_SA(b, h) + aoff + m * 2048 + k * 1024); } while (0)
; #define PG8_MMA(ai, bj, At, Bt) do { __builtin_amdgcn_s_setprio(1); _Pragma("unroll") for (int m = 0; m < 4; ++m) _Pragma("unroll") for (int n = 0; n < 2; ++n) _Pragma("unroll") for (int k = 0; k < 2; ++k) \
;         acc[ai][bj][m][n] = __builtin_amdgcn_mfma_f32_16x16x32_bf16(Bt[n][k], At[m][k], acc[ai][bj][m][n], 0, 0, 0); __builtin_amdgcn_s_setprio(0); } while (0)
; #define PG8_WAIT_V(n) asm volatile("s_waitcnt vmcnt(" #n ")" ::: "memory")
; #define PG8_WAIT_L(n) asm volatile("s_waitcnt lgkmcnt(" #n ")" ::: "memory")
; #define PG8_BAR __builtin_amdgcn_s_barrier()
; #define PG8_SCHED __builtin_amdgcn_sched_barrier(0)
; template <class Epi, class SchedT, bool ALIGN_EPI, bool SP2>
; __device__ __forceinline__ void gemm_phase(LAS unsigned char* lds, const int ldk, const int nt, const SchedT& S, const Epi& E) {
;     ...
;             PG8_LDA(At, 1, 1); PG8_STAGE(PG8_SB(1, 0), b3, voffB); PG8_STAGE(PG8_SB(1, 1), b3 + hstepB, voffB); PG8_STAGE(PG8_SA(1, 0), a3, voffA);
;             PG8_WAIT_V(8); PG8_WAIT_L(0); PG8_BAR; PG8_MMA(1, 0, At, B0); PG8_MMA(1, 1, At, B1); PG8_BAR; PG8_SCHED;
	s_add_i32 s12, s64, s52
	v_lshl_add_u64 v[144:145], v[144:145], 0, s[24:25]
	s_mov_b32 m0, s12
	ds_read_b128 v[190:193], v149 offset:49152
	ds_read_b128 v[194:197], v149 offset:50176
	ds_read_b128 v[198:201], v149 offset:51200
	ds_read_b128 v[202:205], v149 offset:52224
	ds_read_b128 v[206:209], v149 offset:53248
	ds_read_b128 v[210:213], v149 offset:54272
	ds_read_b128 v[214:217], v149 offset:55296
	ds_read_b128 v[218:221], v149 offset:56320
	global_load_lds_dwordx4 v[144:145], off
	s_add_i32 m0, s12, 0x2000
	s_add_u32 s12, s44, 0x56080
	v_lshl_add_u64 v[144:145], v[222:223], 0, s[24:25]
	s_addc_u32 s13, s45, 0
	s_add_i32 s44, s65, s52
	global_load_lds_dwordx4 v[144:145], off
	v_lshl_add_u64 v[144:145], s[12:13], 0, v[0:1]
	s_mov_b32 m0, s44
	s_nop 0
	global_load_lds_dwordx4 v[144:145], off
	v_lshl_add_u64 v[144:145], s[12:13], 0, v[134:135]
	s_add_i32 m0, s44, 0x2000
	s_nop 0
	global_load_lds_dwordx4 v[144:145], off
	v_lshl_add_u64 v[144:145], v[224:225], 0, s[24:25]
	s_mov_b32 m0, s58
	s_nop 0
	global_load_lds_dwordx4 v[144:145], off
	v_lshl_add_u64 v[144:145], v[226:227], 0, s[24:25]
	s_mov_b32 m0, s59
	s_nop 0
	global_load_lds_dwordx4 v[144:145], off
	s_waitcnt vmcnt(8)
	s_waitcnt lgkmcnt(0)
	s_barrier
	s_waitcnt lgkmcnt(0)
	v_mfma_f32_16x16x32_bf16 v[62:65], v[140:143], v[190:193], v[62:65]
	v_mfma_f32_16x16x32_bf16 v[58:61], v[154:157], v[190:193], v[58:61]
	v_mfma_f32_16x16x32_bf16 v[46:49], v[140:143], v[198:201], v[46:49]
	v_mfma_f32_16x16x32_bf16 v[42:45], v[154:157], v[198:201], v[42:45]
	v_mfma_f32_16x16x32_bf16 v[30:33], v[140:143], v[206:209], v[30:33]
	v_mfma_f32_16x16x32_bf16 v[26:29], v[154:157], v[206:209], v[26:29]
	v_mfma_f32_16x16x32_bf16 v[14:17], v[140:143], v[214:217], v[14:17]
	v_mfma_f32_16x16x32_bf16 v[10:13], v[154:157], v[214:217], v[10:13]
	v_mfma_f32_16x16x32_bf16 v[62:65], v[150:153], v[194:197], v[62:65]
	v_mfma_f32_16x16x32_bf16 v[58:61], v[158:161], v[194:197], v[58:61]
	v_mfma_f32_16x16x32_bf16 v[46:49], v[150:153], v[202:205], v[46:49]
	v_mfma_f32_16x16x32_bf16 v[42:45], v[158:161], v[202:205], v[42:45]
	v_mfma_f32_16x16x32_bf16 v[30:33], v[150:153], v[210:213], v[30:33]
	v_mfma_f32_16x16x32_bf16 v[26:29], v[158:161], v[210:213], v[26:29]
	v_mfma_f32_16x16x32_bf16 v[14:17], v[150:153], v[218:221], v[14:17]
	v_mfma_f32_16x16x32_bf16 v[10:13], v[158:161], v[218:221], v[10:13]
	v_mfma_f32_16x16x32_bf16 v[54:57], v[174:177], v[190:193], v[54:57]
	v_mfma_f32_16x16x32_bf16 v[50:53], v[182:185], v[190:193], v[50:53]
	v_mfma_f32_16x16x32_bf16 v[38:41], v[174:177], v[198:201], v[38:41]
	v_mfma_f32_16x16x32_bf16 v[34:37], v[182:185], v[198:201], v[34:37]
	v_mfma_f32_16x16x32_bf16 v[22:25], v[174:177], v[206:209], v[22:25]
	v_mfma_f32_16x16x32_bf16 v[18:21], v[182:185], v[206:209], v[18:21]
	v_mfma_f32_16x16x32_bf16 v[6:9], v[174:177], v[214:217], v[6:9]
	v_mfma_f32_16x16x32_bf16 v[2:5], v[182:185], v[214:217], v[2:5]
	v_mfma_f32_16x16x32_bf16 v[54:57], v[178:181], v[194:197], v[54:57]
	v_mfma_f32_16x16x32_bf16 v[50:53], v[186:189], v[194:197], v[50:53]
	v_mfma_f32_16x16x32_bf16 v[38:41], v[178:181], v[202:205], v[38:41]
	v_mfma_f32_16x16x32_bf16 v[34:37], v[186:189], v[202:205], v[34:37]
	v_mfma_f32_16x16x32_bf16 v[22:25], v[178:181], v[210:213], v[22:25]
	v_mfma_f32_16x16x32_bf16 v[18:21], v[186:189], v[210:213], v[18:21]
	v_mfma_f32_16x16x32_bf16 v[6:9], v[178:181], v[218:221], v[6:9]
	v_mfma_f32_16x16x32_bf16 v[2:5], v[186:189], v[218:221], v[2:5]
	s_barrier
	s_add_i32 s83, s83, 2
	s_add_u32 s81, s81, 0x100
	s_addc_u32 s82, s82, 0
	s_cmpk_gt_u32 s83, 0x53
	s_mov_b64 s[12:13], s[16:17]
